# cross-attention units: one static priority raise (s_setprio 1) for waves 4-7, reset at the phase end
# speedup vs baseline: 1.0025x; 1.0025x over previous
; #define XLAS __attribute__((address_space(3)))
; __device__ __forceinline__ void unit(XLAS unsigned char* lds, const bf16_t* Qg, const bf16_t* Kg, const bf16_t* Vg, bf16_t* Og) {
;     int tid_ = threadIdx.x; asm volatile("" : "+v"(tid_)); const int tid = tid_, lane = tid & 63, r32 = lane & 31, hi = lane >> 5; const int wid = __builtin_amdgcn_readfirstlane(tid >> 6);
;     const int sr = tid >> 4, sseg = tid & 15;
;     const bf16_t* kgp = Kg + (size_t)sr * 4096 + sseg * 16;
;     const bf16_t* vgp = Vg + (size_t)sr * 4096 + sseg * 16;
;     const unsigned wofs = (unsigned)(sr * KP + sseg * 32);
;     ...
;     u32x4 g[2][2];
;     g[0][0] = *(const u32x4*)(XAT_SRC(0)); g[0][1] = *(const u32x4*)(XAT_SRC(0) + 8); g[1][0] = *(const u32x4*)(XAT_SRC(1)); g[1][1] = *(const u32x4*)(XAT_SRC(1) + 8);
;     XLAS unsigned char* xs = lds + XS_OFF + wid * XS_BYTES;
;     bf16x8 qf[16];
; #pragma unroll
;     for (int hq = 0; hq < 2; ++hq) {
;         const bf16_t* qbase = Qg + (size_t)(wid * 32 + (lane >> 4)) * 1024 + hq * 128 + (lane & 15) * 8;
;         u32x4 qv[8];
; #pragma unroll
;         for (int i = 0; i < 8; ++i) qv[i] = *(const u32x4*)(qbase + (size_t)(4 * i) * 1024);
; #pragma unroll
;         for (int i = 0; i < 8; ++i) *(XLAS u32x4*)(xs + (4 * i + (lane >> 4)) * 272 + (lane & 15) * 16) = qv[i];
; #pragma unroll
;         for (int s = 0; s < 8; ++s) qf[hq * 8 + s] = *(const XLAS bf16x8*)(xs + r32 * 272 + s * 32 + hi * 16);
;     }
;     const int krow = (r32 & 0x13) | ((r32 & 4) << 1) | ((r32 & 8) >> 1);
;     const unsigned kro = (unsigned)(krow * KP + hi * 16), vro = (unsigned)(r32 * KP + hi * 16);
;     f32x16 S[8];
; #pragma unroll
;     for (int c = 0; c < 8; ++c) {
;         XLAS unsigned char* buf = lds + (c & 1) * CHB;
;         *(XLAS u32x4*)(buf + wofs) = g[c & 1][0]; *(XLAS u32x4*)(buf + wofs + 16) = g[c & 1][1];
;         __syncthreads();
.LBB0_589:
	s_ashr_i32 s67, s66, 31
	s_ashr_i32 s4, s66, 4
	s_lshl_b64 s[26:27], s[66:67], 19
	s_add_u32 s5, s52, s26
	v_readlane_b32 s8, v255, 39
	s_addc_u32 s16, s53, s27
	s_lshl_b32 s8, s8, 8
	s_ashr_i32 s9, s8, 31
	s_lshl_b64 s[28:29], s[8:9], 1
	s_add_u32 s54, s5, s28
	s_addc_u32 s55, s16, s29
	s_ashr_i32 s5, s4, 31
	s_lshl_b64 s[16:17], s[4:5], 21
	s_add_u32 s5, s3, s16
	s_addc_u32 s9, s7, s17
	s_add_u32 s16, s5, s28
	s_addc_u32 s17, s9, s29
	s_add_i32 s8, s8, s6
	s_ashr_i32 s9, s8, 31
	s_lshl_b64 s[8:9], s[8:9], 13
	s_add_u32 s8, s86, s8
	s_addc_u32 s9, s87, s9
	s_lshl_b32 s4, s4, 8
	s_ashr_i32 s5, s4, 31
	s_lshl_b64 s[4:5], s[4:5], 1
	s_add_u32 s8, s8, s4
	s_addc_u32 s9, s9, s5
	s_add_u32 s4, s50, s26
	s_addc_u32 s5, s51, s27
	v_mov_b32_e32 v215, v206
	s_add_u32 s4, s4, s28
	s_addc_u32 s5, s5, s29
	v_readfirstlane_b32 s26, v215
	s_ashr_i32 s27, s26, 6
	s_lshl_b32 s26, s27, 5
	s_cmp_lt_u32 s27, 4
	s_cbranch_scc1 .Lxprio_skip
	s_setprio 1
.Lxprio_skip:
	v_bfe_u32 v90, v215, 4, 2
	v_or_b32_e32 v2, s26, v90
	v_ashrrev_i32_e32 v3, 31, v2
	v_and_b32_e32 v80, 15, v215
	v_lshlrev_b64 v[2:3], 11, v[2:3]
	v_lshlrev_b32_e32 v0, 4, v80
	v_lshl_add_u64 v[2:3], s[54:55], 0, v[2:3]
	v_lshl_add_u64 v[6:7], v[2:3], 0, v[0:1]
	v_add_co_u32_e32 v8, vcc, s33, v6
	s_movk_i32 s28, 0x4000
	s_nop 0
	v_addc_co_u32_e32 v9, vcc, 0, v7, vcc
	v_add_co_u32_e32 v10, vcc, s28, v6
	s_mov_b32 s29, 0x8000
	s_nop 0
	v_addc_co_u32_e32 v11, vcc, 0, v7, vcc
	v_add_co_u32_e32 v12, vcc, s2, v6
	s_mov_b32 s42, 0xc000
	s_nop 0
	v_addc_co_u32_e32 v13, vcc, 0, v7, vcc
	v_add_co_u32_e32 v14, vcc, s29, v6
	s_mov_b32 s44, 0xe000
	s_nop 0
	v_addc_co_u32_e32 v15, vcc, 0, v7, vcc
	v_add_co_u32_e32 v16, vcc, s1, v6
	v_ashrrev_i32_e32 v88, 4, v215
	s_nop 0
	v_addc_co_u32_e32 v17, vcc, 0, v7, vcc
	v_add_co_u32_e32 v18, vcc, s42, v6
	v_ashrrev_i32_e32 v89, 31, v88
	s_nop 0
	v_addc_co_u32_e32 v19, vcc, 0, v7, vcc
	v_add_co_u32_e32 v76, vcc, s44, v6
	global_load_dwordx4 v[2:5], v[6:7], off
	global_load_dwordx4 v[20:23], v[8:9], off
	v_addc_co_u32_e32 v77, vcc, 0, v7, vcc
	global_load_dwordx4 v[24:27], v[10:11], off
	global_load_dwordx4 v[28:31], v[12:13], off
	global_load_dwordx4 v[32:35], v[14:15], off
	global_load_dwordx4 v[36:39], v[16:17], off
	global_load_dwordx4 v[40:43], v[18:19], off
	global_load_dwordx4 v[44:47], v[76:77], off
	global_load_dwordx4 v[48:51], v[6:7], off offset:256
	global_load_dwordx4 v[52:55], v[8:9], off offset:256
	global_load_dwordx4 v[56:59], v[10:11], off offset:256
	global_load_dwordx4 v[60:63], v[12:13], off offset:256
	global_load_dwordx4 v[64:67], v[14:15], off offset:256
	global_load_dwordx4 v[68:71], v[16:17], off offset:256
	global_load_dwordx4 v[72:75], v[18:19], off offset:256
	s_nop 0
	global_load_dwordx4 v[76:79], v[76:77], off offset:256
	v_lshlrev_b64 v[16:17], 13, v[88:89]
	v_lshl_add_u64 v[6:7], s[16:17], 0, v[16:17]
	v_lshlrev_b32_e32 v18, 5, v80
	v_mov_b32_e32 v19, v1
	v_lshl_add_u64 v[14:15], v[6:7], 0, v[18:19]
	global_load_dwordx4 v[80:83], v[14:15], off
	global_load_dwordx4 v[84:87], v[14:15], off offset:16
	s_mulk_i32 s27, 0x2200
	v_and_b32_e32 v216, 31, v215
	v_bfe_u32 v217, v215, 5, 1
	v_add_co_u32_e32 v8, vcc, s45, v14
	s_add_i32 s16, s27, 0
	v_mul_u32_u24_e32 v90, 0x110, v90
	v_lshl_add_u64 v[6:7], v[14:15], 0, s[22:23]
	v_addc_co_u32_e32 v9, vcc, 0, v15, vcc
	v_mul_u32_u24_e32 v89, 0x110, v216
	v_lshlrev_b32_e32 v218, 4, v217
	v_add3_u32 v0, s16, v0, v90
	global_load_dwordx4 v[10:13], v[8:9], off
	s_nop 0
	global_load_dwordx4 v[6:9], v[6:7], off offset:16
	v_add3_u32 v89, s16, v89, v218
	s_movk_i32 s17, 0x210
	v_lshl_add_u64 v[16:17], s[8:9], 0, v[16:17]
	v_lshl_add_u64 v[212:213], v[16:17], 0, v[18:19]
	s_waitcnt vmcnt(19)
	ds_write_b128 v0, v[2:5] offset:34816
	s_waitcnt vmcnt(18)
	ds_write_b128 v0, v[20:23] offset:35904
	s_waitcnt vmcnt(17)
	ds_write_b128 v0, v[24:27] offset:36992
	s_waitcnt vmcnt(16)
	ds_write_b128 v0, v[28:31] offset:38080
	s_waitcnt vmcnt(15)
	ds_write_b128 v0, v[32:35] offset:39168
	s_waitcnt vmcnt(14)
	ds_write_b128 v0, v[36:39] offset:40256
	s_waitcnt vmcnt(13)
	ds_write_b128 v0, v[40:43] offset:41344
	s_waitcnt vmcnt(12)
	ds_write_b128 v0, v[44:47] offset:42432
	ds_read_b128 v[2:5], v89 offset:34816
	ds_read_b128 v[170:173], v89 offset:34848
	ds_read_b128 v[166:169], v89 offset:34880
	ds_read_b128 v[162:165], v89 offset:34912
	ds_read_b128 v[158:161], v89 offset:34944
	ds_read_b128 v[154:157], v89 offset:34976
	ds_read_b128 v[134:137], v89 offset:35008
	ds_read_b128 v[130:133], v89 offset:35040
	s_waitcnt vmcnt(11)
	ds_write_b128 v0, v[48:51] offset:34816
	s_waitcnt vmcnt(10)
	ds_write_b128 v0, v[52:55] offset:35904
	s_waitcnt vmcnt(9)
	ds_write_b128 v0, v[56:59] offset:36992
	s_waitcnt vmcnt(8)
	ds_write_b128 v0, v[60:63] offset:38080
	s_waitcnt vmcnt(7)
	ds_write_b128 v0, v[64:67] offset:39168
	s_waitcnt vmcnt(6)
	ds_write_b128 v0, v[68:71] offset:40256
	s_waitcnt vmcnt(5)
	ds_write_b128 v0, v[72:75] offset:41344
	s_waitcnt vmcnt(4)
	ds_write_b128 v0, v[76:79] offset:42432
	v_mul_lo_u32 v0, v88, s17
	v_add_co_u32_e32 v22, vcc, s46, v14
	v_add3_u32 v214, v0, v18, 0
	s_nop 0
	v_addc_co_u32_e32 v23, vcc, 0, v15, vcc
	ds_read_b128 v[202:205], v89 offset:34816
	ds_read_b128 v[198:201], v89 offset:34848
	ds_read_b128 v[194:197], v89 offset:34880
	ds_read_b128 v[190:193], v89 offset:34912
	ds_read_b128 v[186:189], v89 offset:34944
	ds_read_b128 v[182:185], v89 offset:34976
	ds_read_b128 v[178:181], v89 offset:35008
	ds_read_b128 v[174:177], v89 offset:35040
	s_waitcnt vmcnt(3)
	ds_write_b128 v214, v[80:83]
	s_waitcnt vmcnt(2)
	ds_write_b128 v214, v[84:87] offset:16
	s_waitcnt lgkmcnt(0)
	s_barrier
; #define XLAS __attribute__((address_space(3)))
; __device__ __forceinline__ void unit(XLAS unsigned char* lds, const bf16_t* Qg, const bf16_t* Kg, const bf16_t* Vg, bf16_t* Og) {
;     ...
;     for (int c = 0; c < 8; ++c) {
;         XLAS unsigned char* buf = lds + (c & 1) * CHB;
;         *(XLAS u32x4*)(buf + wofs) = g[c & 1][0]; *(XLAS u32x4*)(buf + wofs + 16) = g[c & 1][1];
;         __syncthreads();
;         { g[c & 1][0] = *(const u32x4*)(XAT_SRC(c + 2)); g[c & 1][1] = *(const u32x4*)(XAT_SRC(c + 2) + 8); }
;         f32x16 a = {};
;         bf16x8 kfa[4], kfb[4];
; #pragma unroll
;         for (int j = 0; j < 4; ++j) kfa[j] = *(const XLAS bf16x8*)(buf + kro + j * 32);
; #pragma unroll
;         for (int gq = 0; gq < 4; gq += 2) {
; #pragma unroll
;             for (int j = 0; j < 4; ++j) kfb[j] = *(const XLAS bf16x8*)(buf + kro + (4 * gq + 4 + j) * 32);
;             __builtin_amdgcn_sched_barrier(0);
; #pragma unroll
;             for (int j = 0; j < 4; ++j) a = __builtin_amdgcn_mfma_f32_32x32x16_bf16(kfa[j], qf[4 * gq + j], a, 0, 0, 0);
;             if (gq < 2) {
; #pragma unroll
;                 for (int j = 0; j < 4; ++j) kfa[j] = *(const XLAS bf16x8*)(buf + kro + (4 * gq + 8 + j) * 32); }
;             __builtin_amdgcn_sched_barrier(0);
; #pragma unroll
;             for (int j = 0; j < 4; ++j) a = __builtin_amdgcn_mfma_f32_32x32x16_bf16(kfb[j], qf[4 * gq + 4 + j], a, 0, 0, 0);
;         }
;         S[c] = a;
;     }
	v_lshl_add_u64 v[20:21], v[14:15], 0, s[34:35]
	global_load_dwordx4 v[50:53], v[22:23], off
	global_load_dwordx4 v[54:57], v[20:21], off offset:16
	v_lshlrev_b32_e32 v20, 1, v215
	v_lshrrev_b32_e32 v21, 1, v215
	v_and_b32_e32 v0, 19, v215
	v_and_b32_e32 v20, 8, v20
	v_and_b32_e32 v21, 4, v21
	v_or3_b32 v0, v0, v20, v21
	v_mul_u32_u24_e32 v0, 0x210, v0
	v_add3_u32 v0, v0, v218, 0
	ds_read_b128 v[20:23], v0
	ds_read_b128 v[34:37], v0 offset:32
	ds_read_b128 v[38:41], v0 offset:64
	ds_read_b128 v[42:45], v0 offset:96
	ds_read_b128 v[46:49], v0 offset:128
	ds_read_b128 v[58:61], v0 offset:160
	ds_read_b128 v[62:65], v0 offset:192
	ds_read_b128 v[66:69], v0 offset:224
	s_waitcnt lgkmcnt(7)
	v_mfma_f32_32x32x16_bf16 v[18:33], v[20:23], v[2:5], 0
	s_waitcnt lgkmcnt(6)
	v_mfma_f32_32x32x16_bf16 v[18:33], v[34:37], v[170:173], v[18:33]
	s_waitcnt lgkmcnt(5)
	v_mfma_f32_32x32x16_bf16 v[18:33], v[38:41], v[166:169], v[18:33]
	ds_read_b128 v[34:37], v0 offset:352
	ds_read_b128 v[38:41], v0 offset:320
	ds_read_b128 v[70:73], v0 offset:256
	ds_read_b128 v[74:77], v0 offset:288
	s_waitcnt lgkmcnt(8)
	v_mfma_f32_32x32x16_bf16 v[18:33], v[42:45], v[162:165], v[18:33]
	s_waitcnt lgkmcnt(7)
	v_mfma_f32_32x32x16_bf16 v[18:33], v[46:49], v[158:161], v[18:33]
	s_waitcnt lgkmcnt(6)
	v_mfma_f32_32x32x16_bf16 v[18:33], v[58:61], v[154:157], v[18:33]
	s_waitcnt lgkmcnt(5)
	v_mfma_f32_32x32x16_bf16 v[18:33], v[62:65], v[134:137], v[18:33]
	ds_read_b128 v[42:45], v0 offset:384
	ds_read_b128 v[46:49], v0 offset:416
	ds_read_b128 v[58:61], v0 offset:448
	ds_read_b128 v[62:65], v0 offset:480
	s_waitcnt lgkmcnt(8)
	v_mfma_f32_32x32x16_bf16 v[18:33], v[66:69], v[130:133], v[18:33]
	s_waitcnt lgkmcnt(5)
	v_mfma_f32_32x32x16_bf16 v[18:33], v[70:73], v[202:205], v[18:33]
	s_waitcnt lgkmcnt(4)
	v_mfma_f32_32x32x16_bf16 v[18:33], v[74:77], v[198:201], v[18:33]
	v_mfma_f32_32x32x16_bf16 v[18:33], v[38:41], v[194:197], v[18:33]
	v_mfma_f32_32x32x16_bf16 v[18:33], v[34:37], v[190:193], v[18:33]
	s_waitcnt vmcnt(3)
	ds_write_b128 v214, v[10:13] offset:16896
	s_waitcnt vmcnt(2)
	ds_write_b128 v214, v[6:9] offset:16912
	v_add_co_u32_e32 v6, vcc, s47, v14
	v_lshl_add_u64 v[10:11], v[14:15], 0, s[36:37]
	s_nop 0
	v_addc_co_u32_e32 v7, vcc, 0, v15, vcc
	s_waitcnt lgkmcnt(0)
	s_barrier
	global_load_dwordx4 v[6:9], v[6:7], off
	s_nop 0
	global_load_dwordx4 v[10:13], v[10:11], off offset:16
	v_mfma_f32_32x32x16_bf16 v[18:33], v[42:45], v[186:189], v[18:33]
	v_mfma_f32_32x32x16_bf16 v[18:33], v[46:49], v[182:185], v[18:33]
	v_mfma_f32_32x32x16_bf16 v[18:33], v[58:61], v[178:181], v[18:33]
	ds_read_b128 v[34:37], v0 offset:16896
	ds_read_b128 v[58:61], v0 offset:16928
	ds_read_b128 v[66:69], v0 offset:16960
	ds_read_b128 v[70:73], v0 offset:16992
	ds_read_b128 v[74:77], v0 offset:17024
	ds_read_b128 v[78:81], v0 offset:17056
	ds_read_b128 v[82:85], v0 offset:17088
	ds_read_b128 v[86:89], v0 offset:17120
	v_mfma_f32_32x32x16_bf16 v[18:33], v[62:65], v[174:177], v[18:33]
	s_waitcnt lgkmcnt(7)
	v_mfma_f32_32x32x16_bf16 v[34:49], v[34:37], v[2:5], 0
	s_waitcnt lgkmcnt(6)
	v_mfma_f32_32x32x16_bf16 v[34:49], v[58:61], v[170:173], v[34:49]
	s_waitcnt lgkmcnt(5)
	v_mfma_f32_32x32x16_bf16 v[34:49], v[66:69], v[166:169], v[34:49]
	ds_read_b128 v[58:61], v0 offset:17248
	ds_read_b128 v[62:65], v0 offset:17216
	ds_read_b128 v[66:69], v0 offset:17152
	ds_read_b128 v[90:93], v0 offset:17184
	s_waitcnt lgkmcnt(8)
	v_mfma_f32_32x32x16_bf16 v[34:49], v[70:73], v[162:165], v[34:49]
	s_waitcnt lgkmcnt(7)
	v_mfma_f32_32x32x16_bf16 v[34:49], v[74:77], v[158:161], v[34:49]
	s_waitcnt lgkmcnt(6)
	v_mfma_f32_32x32x16_bf16 v[34:49], v[78:81], v[154:157], v[34:49]
	s_waitcnt lgkmcnt(5)
	v_mfma_f32_32x32x16_bf16 v[34:49], v[82:85], v[134:137], v[34:49]
	ds_read_b128 v[70:73], v0 offset:17280
	ds_read_b128 v[74:77], v0 offset:17312
	ds_read_b128 v[78:81], v0 offset:17344
	ds_read_b128 v[82:85], v0 offset:17376
	s_waitcnt lgkmcnt(8)
	v_mfma_f32_32x32x16_bf16 v[34:49], v[86:89], v[130:133], v[34:49]
	s_waitcnt lgkmcnt(5)
	v_mfma_f32_32x32x16_bf16 v[34:49], v[66:69], v[202:205], v[34:49]
	s_waitcnt lgkmcnt(4)
	v_mfma_f32_32x32x16_bf16 v[34:49], v[90:93], v[198:201], v[34:49]
	v_mfma_f32_32x32x16_bf16 v[34:49], v[62:65], v[194:197], v[34:49]
	v_mfma_f32_32x32x16_bf16 v[34:49], v[58:61], v[190:193], v[34:49]
	s_mov_b32 s17, 0x100000
	s_waitcnt vmcnt(3)
	ds_write_b128 v214, v[50:53]
	s_waitcnt vmcnt(2)
	ds_write_b128 v214, v[54:57] offset:16
	v_add_co_u32_e32 v50, vcc, s17, v14
	s_waitcnt lgkmcnt(0)
	s_nop 0
	v_addc_co_u32_e32 v51, vcc, 0, v15, vcc
	s_barrier
; #define XLAS __attribute__((address_space(3)))
; __device__ __forceinline__ void unit(XLAS unsigned char* lds, const bf16_t* Qg, const bf16_t* Kg, const bf16_t* Vg, bf16_t* Og) {
;     ...
;     for (int c = 0; c < 8; ++c) {
;         XLAS unsigned char* buf = lds + (c & 1) * CHB;
;         *(XLAS u32x4*)(buf + wofs) = g[c & 1][0]; *(XLAS u32x4*)(buf + wofs + 16) = g[c & 1][1];
;         __syncthreads();
;         { g[c & 1][0] = *(const u32x4*)(XAT_SRC(c + 2)); g[c & 1][1] = *(const u32x4*)(XAT_SRC(c + 2) + 8); }
;         f32x16 a = {};
;         bf16x8 kfa[4], kfb[4];
; #pragma unroll
;         for (int j = 0; j < 4; ++j) kfa[j] = *(const XLAS bf16x8*)(buf + kro + j * 32);
; #pragma unroll
;         for (int gq = 0; gq < 4; gq += 2) {
; #pragma unroll
;             for (int j = 0; j < 4; ++j) kfb[j] = *(const XLAS bf16x8*)(buf + kro + (4 * gq + 4 + j) * 32);
;             __builtin_amdgcn_sched_barrier(0);
; #pragma unroll
;             for (int j = 0; j < 4; ++j) a = __builtin_amdgcn_mfma_f32_32x32x16_bf16(kfa[j], qf[4 * gq + j], a, 0, 0, 0);
;             if (gq < 2) {
; #pragma unroll
;                 for (int j = 0; j < 4; ++j) kfa[j] = *(const XLAS bf16x8*)(buf + kro + (4 * gq + 8 + j) * 32); }
;             __builtin_amdgcn_sched_barrier(0);
; #pragma unroll
;             for (int j = 0; j < 4; ++j) a = __builtin_amdgcn_mfma_f32_32x32x16_bf16(kfb[j], qf[4 * gq + 4 + j], a, 0, 0, 0);
;         }
;         S[c] = a;
;     }
	v_lshl_add_u64 v[16:17], v[14:15], 0, s[30:31]
	global_load_dwordx4 v[86:89], v[50:51], off
	global_load_dwordx4 v[90:93], v[16:17], off offset:16
	v_mfma_f32_32x32x16_bf16 v[34:49], v[70:73], v[186:189], v[34:49]
	v_mfma_f32_32x32x16_bf16 v[34:49], v[74:77], v[182:185], v[34:49]
	v_mfma_f32_32x32x16_bf16 v[34:49], v[78:81], v[178:181], v[34:49]
	ds_read_b128 v[50:53], v0
	ds_read_b128 v[66:69], v0 offset:32
	ds_read_b128 v[70:73], v0 offset:64
	ds_read_b128 v[74:77], v0 offset:96
	ds_read_b128 v[78:81], v0 offset:128
	ds_read_b128 v[94:97], v0 offset:160
	ds_read_b128 v[98:101], v0 offset:192
	ds_read_b128 v[102:105], v0 offset:224
	v_mfma_f32_32x32x16_bf16 v[34:49], v[82:85], v[174:177], v[34:49]
	s_waitcnt lgkmcnt(7)
	v_mfma_f32_32x32x16_bf16 v[50:65], v[50:53], v[2:5], 0
	s_waitcnt lgkmcnt(6)
	v_mfma_f32_32x32x16_bf16 v[50:65], v[66:69], v[170:173], v[50:65]
	s_waitcnt lgkmcnt(5)
	v_mfma_f32_32x32x16_bf16 v[50:65], v[70:73], v[166:169], v[50:65]
	ds_read_b128 v[66:69], v0 offset:352
	ds_read_b128 v[70:73], v0 offset:320
	ds_read_b128 v[82:85], v0 offset:256
	ds_read_b128 v[106:109], v0 offset:288
	s_waitcnt lgkmcnt(8)
	v_mfma_f32_32x32x16_bf16 v[50:65], v[74:77], v[162:165], v[50:65]
	s_waitcnt lgkmcnt(7)
	v_mfma_f32_32x32x16_bf16 v[50:65], v[78:81], v[158:161], v[50:65]
	s_waitcnt lgkmcnt(6)
	v_mfma_f32_32x32x16_bf16 v[50:65], v[94:97], v[154:157], v[50:65]
	s_waitcnt lgkmcnt(5)
	v_mfma_f32_32x32x16_bf16 v[50:65], v[98:101], v[134:137], v[50:65]
	ds_read_b128 v[74:77], v0 offset:384
	ds_read_b128 v[78:81], v0 offset:416
	ds_read_b128 v[94:97], v0 offset:448
	ds_read_b128 v[98:101], v0 offset:480
	s_waitcnt lgkmcnt(8)
	v_mfma_f32_32x32x16_bf16 v[50:65], v[102:105], v[130:133], v[50:65]
	s_waitcnt lgkmcnt(5)
	v_mfma_f32_32x32x16_bf16 v[50:65], v[82:85], v[202:205], v[50:65]
	s_waitcnt lgkmcnt(4)
	v_mfma_f32_32x32x16_bf16 v[50:65], v[106:109], v[198:201], v[50:65]
	v_mfma_f32_32x32x16_bf16 v[50:65], v[70:73], v[194:197], v[50:65]
	v_mfma_f32_32x32x16_bf16 v[50:65], v[66:69], v[190:193], v[50:65]
	s_mov_b32 s27, 0x140000
	s_waitcnt vmcnt(3)
	ds_write_b128 v214, v[6:9] offset:16896
	s_waitcnt vmcnt(2)
	ds_write_b128 v214, v[10:13] offset:16912
	v_add_co_u32_e32 v6, vcc, s27, v14
	v_lshl_add_u64 v[10:11], v[14:15], 0, s[38:39]
	s_nop 0
	v_addc_co_u32_e32 v7, vcc, 0, v15, vcc
	s_waitcnt lgkmcnt(0)
	s_barrier
	global_load_dwordx4 v[6:9], v[6:7], off
	s_nop 0
	global_load_dwordx4 v[10:13], v[10:11], off offset:16
	v_mfma_f32_32x32x16_bf16 v[50:65], v[74:77], v[186:189], v[50:65]
	v_mfma_f32_32x32x16_bf16 v[50:65], v[78:81], v[182:185], v[50:65]
	v_mfma_f32_32x32x16_bf16 v[50:65], v[94:97], v[178:181], v[50:65]
	ds_read_b128 v[66:69], v0 offset:16896
	ds_read_b128 v[82:85], v0 offset:16928
	ds_read_b128 v[94:97], v0 offset:16960
	ds_read_b128 v[102:105], v0 offset:16992
	ds_read_b128 v[106:109], v0 offset:17024
	ds_read_b128 v[110:113], v0 offset:17056
	ds_read_b128 v[114:117], v0 offset:17088
	ds_read_b128 v[118:121], v0 offset:17120
	v_mfma_f32_32x32x16_bf16 v[50:65], v[98:101], v[174:177], v[50:65]
	s_waitcnt lgkmcnt(7)
	v_mfma_f32_32x32x16_bf16 v[66:81], v[66:69], v[2:5], 0
	s_waitcnt lgkmcnt(6)
	v_mfma_f32_32x32x16_bf16 v[66:81], v[82:85], v[170:173], v[66:81]
	s_waitcnt lgkmcnt(5)
	v_mfma_f32_32x32x16_bf16 v[66:81], v[94:97], v[166:169], v[66:81]
	ds_read_b128 v[82:85], v0 offset:17248
	ds_read_b128 v[94:97], v0 offset:17216
	ds_read_b128 v[98:101], v0 offset:17152
	ds_read_b128 v[122:125], v0 offset:17184
	s_waitcnt lgkmcnt(8)
	v_mfma_f32_32x32x16_bf16 v[66:81], v[102:105], v[162:165], v[66:81]
	s_waitcnt lgkmcnt(7)
	v_mfma_f32_32x32x16_bf16 v[66:81], v[106:109], v[158:161], v[66:81]
	s_waitcnt lgkmcnt(6)
	v_mfma_f32_32x32x16_bf16 v[66:81], v[110:113], v[154:157], v[66:81]
	s_waitcnt lgkmcnt(5)
	v_mfma_f32_32x32x16_bf16 v[66:81], v[114:117], v[134:137], v[66:81]
	ds_read_b128 v[102:105], v0 offset:17280
	ds_read_b128 v[106:109], v0 offset:17312
	ds_read_b128 v[110:113], v0 offset:17344
	ds_read_b128 v[114:117], v0 offset:17376
	s_waitcnt lgkmcnt(8)
	v_mfma_f32_32x32x16_bf16 v[66:81], v[118:121], v[130:133], v[66:81]
	s_waitcnt lgkmcnt(5)
	v_mfma_f32_32x32x16_bf16 v[66:81], v[98:101], v[202:205], v[66:81]
	s_waitcnt lgkmcnt(4)
	v_mfma_f32_32x32x16_bf16 v[66:81], v[122:125], v[198:201], v[66:81]
	v_mfma_f32_32x32x16_bf16 v[66:81], v[94:97], v[194:197], v[66:81]
	v_mfma_f32_32x32x16_bf16 v[66:81], v[82:85], v[190:193], v[66:81]
	v_add_co_u32_e32 v82, vcc, s58, v14
	s_waitcnt vmcnt(3)
	ds_write_b128 v214, v[86:89]
	s_waitcnt vmcnt(2)
	ds_write_b128 v214, v[90:93] offset:16
	v_addc_co_u32_e32 v83, vcc, 0, v15, vcc
	s_waitcnt lgkmcnt(0)
	s_barrier
; #define XLAS __attribute__((address_space(3)))
; __device__ __forceinline__ void unit(XLAS unsigned char* lds, const bf16_t* Qg, const bf16_t* Kg, const bf16_t* Vg, bf16_t* Og) {
;     ...
;     for (int c = 0; c < 8; ++c) {
;         XLAS unsigned char* buf = lds + (c & 1) * CHB;
;         *(XLAS u32x4*)(buf + wofs) = g[c & 1][0]; *(XLAS u32x4*)(buf + wofs + 16) = g[c & 1][1];
;         __syncthreads();
;         { g[c & 1][0] = *(const u32x4*)(XAT_SRC(c + 2)); g[c & 1][1] = *(const u32x4*)(XAT_SRC(c + 2) + 8); }
;         f32x16 a = {};
;         bf16x8 kfa[4], kfb[4];
; #pragma unroll
;         for (int j = 0; j < 4; ++j) kfa[j] = *(const XLAS bf16x8*)(buf + kro + j * 32);
; #pragma unroll
;         for (int gq = 0; gq < 4; gq += 2) {
; #pragma unroll
;             for (int j = 0; j < 4; ++j) kfb[j] = *(const XLAS bf16x8*)(buf + kro + (4 * gq + 4 + j) * 32);
;             __builtin_amdgcn_sched_barrier(0);
; #pragma unroll
;             for (int j = 0; j < 4; ++j) a = __builtin_amdgcn_mfma_f32_32x32x16_bf16(kfa[j], qf[4 * gq + j], a, 0, 0, 0);
;             if (gq < 2) {
; #pragma unroll
;                 for (int j = 0; j < 4; ++j) kfa[j] = *(const XLAS bf16x8*)(buf + kro + (4 * gq + 8 + j) * 32); }
;             __builtin_amdgcn_sched_barrier(0);
; #pragma unroll
;             for (int j = 0; j < 4; ++j) a = __builtin_amdgcn_mfma_f32_32x32x16_bf16(kfb[j], qf[4 * gq + 4 + j], a, 0, 0, 0);
;         }
;         S[c] = a;
;     }
	v_lshl_add_u64 v[16:17], v[14:15], 0, s[56:57]
	global_load_dwordx4 v[118:121], v[82:83], off
	global_load_dwordx4 v[122:125], v[16:17], off offset:16
	v_mfma_f32_32x32x16_bf16 v[66:81], v[102:105], v[186:189], v[66:81]
	v_mfma_f32_32x32x16_bf16 v[66:81], v[106:109], v[182:185], v[66:81]
	v_mfma_f32_32x32x16_bf16 v[66:81], v[110:113], v[178:181], v[66:81]
	ds_read_b128 v[82:85], v0
	ds_read_b128 v[98:101], v0 offset:32
	ds_read_b128 v[102:105], v0 offset:64
	ds_read_b128 v[106:109], v0 offset:96
	ds_read_b128 v[110:113], v0 offset:128
	ds_read_b128 v[126:129], v0 offset:160
	ds_read_b128 v[138:141], v0 offset:192
	ds_read_b128 v[142:145], v0 offset:224
	v_mfma_f32_32x32x16_bf16 v[66:81], v[114:117], v[174:177], v[66:81]
	s_waitcnt lgkmcnt(7)
	v_mfma_f32_32x32x16_bf16 v[82:97], v[82:85], v[2:5], 0
	s_waitcnt lgkmcnt(6)
	v_mfma_f32_32x32x16_bf16 v[82:97], v[98:101], v[170:173], v[82:97]
	s_waitcnt lgkmcnt(5)
	v_mfma_f32_32x32x16_bf16 v[82:97], v[102:105], v[166:169], v[82:97]
	ds_read_b128 v[98:101], v0 offset:352
	ds_read_b128 v[102:105], v0 offset:320
	ds_read_b128 v[114:117], v0 offset:256
	ds_read_b128 v[146:149], v0 offset:288
	s_waitcnt lgkmcnt(8)
	v_mfma_f32_32x32x16_bf16 v[82:97], v[106:109], v[162:165], v[82:97]
	s_waitcnt lgkmcnt(7)
	v_mfma_f32_32x32x16_bf16 v[82:97], v[110:113], v[158:161], v[82:97]
	s_waitcnt lgkmcnt(6)
	v_mfma_f32_32x32x16_bf16 v[82:97], v[126:129], v[154:157], v[82:97]
	s_waitcnt lgkmcnt(5)
	v_mfma_f32_32x32x16_bf16 v[82:97], v[138:141], v[134:137], v[82:97]
	ds_read_b128 v[106:109], v0 offset:384
	ds_read_b128 v[110:113], v0 offset:416
	ds_read_b128 v[126:129], v0 offset:448
	ds_read_b128 v[138:141], v0 offset:480
	s_waitcnt lgkmcnt(8)
	v_mfma_f32_32x32x16_bf16 v[82:97], v[142:145], v[130:133], v[82:97]
	s_waitcnt lgkmcnt(5)
	v_mfma_f32_32x32x16_bf16 v[82:97], v[114:117], v[202:205], v[82:97]
	s_waitcnt lgkmcnt(4)
	v_mfma_f32_32x32x16_bf16 v[82:97], v[146:149], v[198:201], v[82:97]
	v_mfma_f32_32x32x16_bf16 v[82:97], v[102:105], v[194:197], v[82:97]
	v_mfma_f32_32x32x16_bf16 v[82:97], v[98:101], v[190:193], v[82:97]
	s_waitcnt vmcnt(3)
	ds_write_b128 v214, v[6:9] offset:16896
	s_waitcnt vmcnt(2)
	ds_write_b128 v214, v[10:13] offset:16912
	v_add_co_u32_e32 v6, vcc, s59, v14
	v_lshl_add_u64 v[10:11], v[14:15], 0, s[60:61]
	s_nop 0
	v_addc_co_u32_e32 v7, vcc, 0, v15, vcc
	s_waitcnt lgkmcnt(0)
	s_barrier
	global_load_dwordx4 v[6:9], v[6:7], off
	s_nop 0
	global_load_dwordx4 v[10:13], v[10:11], off offset:16
	v_mfma_f32_32x32x16_bf16 v[82:97], v[106:109], v[186:189], v[82:97]
	v_mfma_f32_32x32x16_bf16 v[82:97], v[110:113], v[182:185], v[82:97]
	v_mfma_f32_32x32x16_bf16 v[82:97], v[126:129], v[178:181], v[82:97]
	ds_read_b128 v[14:17], v0 offset:16896
	ds_read_b128 v[114:117], v0 offset:16928
	ds_read_b128 v[126:129], v0 offset:16960
	ds_read_b128 v[142:145], v0 offset:16992
	ds_read_b128 v[146:149], v0 offset:17024
	ds_read_b128 v[150:153], v0 offset:17056
	ds_read_b128 v[220:223], v0 offset:17088
	ds_read_b128 v[224:227], v0 offset:17120
	v_mfma_f32_32x32x16_bf16 v[82:97], v[138:141], v[174:177], v[82:97]
	s_waitcnt lgkmcnt(7)
	v_mfma_f32_32x32x16_bf16 v[98:113], v[14:17], v[2:5], 0
	s_waitcnt lgkmcnt(6)
	v_mfma_f32_32x32x16_bf16 v[98:113], v[114:117], v[170:173], v[98:113]
	s_waitcnt lgkmcnt(5)
	v_mfma_f32_32x32x16_bf16 v[98:113], v[126:129], v[166:169], v[98:113]
	ds_read_b128 v[14:17], v0 offset:17248
	ds_read_b128 v[114:117], v0 offset:17216
	ds_read_b128 v[126:129], v0 offset:17152
	ds_read_b128 v[138:141], v0 offset:17184
	s_waitcnt lgkmcnt(8)
	v_mfma_f32_32x32x16_bf16 v[98:113], v[142:145], v[162:165], v[98:113]
	s_waitcnt lgkmcnt(7)
	v_mfma_f32_32x32x16_bf16 v[98:113], v[146:149], v[158:161], v[98:113]
	s_waitcnt lgkmcnt(6)
	v_mfma_f32_32x32x16_bf16 v[98:113], v[150:153], v[154:157], v[98:113]
	s_waitcnt lgkmcnt(5)
	v_mfma_f32_32x32x16_bf16 v[98:113], v[220:223], v[134:137], v[98:113]
	ds_read_b128 v[142:145], v0 offset:17280
	ds_read_b128 v[146:149], v0 offset:17312
	ds_read_b128 v[220:223], v0 offset:17344
	ds_read_b128 v[228:231], v0 offset:17376
	s_waitcnt lgkmcnt(8)
	v_mfma_f32_32x32x16_bf16 v[98:113], v[224:227], v[130:133], v[98:113]
	s_waitcnt lgkmcnt(5)
	v_mfma_f32_32x32x16_bf16 v[98:113], v[126:129], v[202:205], v[98:113]
	s_waitcnt lgkmcnt(4)
	v_mfma_f32_32x32x16_bf16 v[98:113], v[138:141], v[198:201], v[98:113]
	v_mfma_f32_32x32x16_bf16 v[98:113], v[114:117], v[194:197], v[98:113]
	v_mfma_f32_32x32x16_bf16 v[98:113], v[14:17], v[190:193], v[98:113]
	s_waitcnt lgkmcnt(3)
	v_mfma_f32_32x32x16_bf16 v[98:113], v[142:145], v[186:189], v[98:113]
	s_waitcnt vmcnt(3)
	ds_write_b128 v214, v[118:121]
	s_waitcnt vmcnt(2)
	ds_write_b128 v214, v[122:125] offset:16
	s_waitcnt lgkmcnt(0)
	s_barrier
; #define XLAS __attribute__((address_space(3)))
; __device__ __forceinline__ void unit(XLAS unsigned char* lds, const bf16_t* Qg, const bf16_t* Kg, const bf16_t* Vg, bf16_t* Og) {
;     ...
;     for (int c = 0; c < 8; ++c) {
;         XLAS unsigned char* buf = lds + (c & 1) * CHB;
;         *(XLAS u32x4*)(buf + wofs) = g[c & 1][0]; *(XLAS u32x4*)(buf + wofs + 16) = g[c & 1][1];
;         __syncthreads();
;         { g[c & 1][0] = *(const u32x4*)(XAT_SRC(c + 2)); g[c & 1][1] = *(const u32x4*)(XAT_SRC(c + 2) + 8); }
;         f32x16 a = {};
;         bf16x8 kfa[4], kfb[4];
; #pragma unroll
;         for (int j = 0; j < 4; ++j) kfa[j] = *(const XLAS bf16x8*)(buf + kro + j * 32);
; #pragma unroll
;         for (int gq = 0; gq < 4; gq += 2) {
; #pragma unroll
;             for (int j = 0; j < 4; ++j) kfb[j] = *(const XLAS bf16x8*)(buf + kro + (4 * gq + 4 + j) * 32);
;             __builtin_amdgcn_sched_barrier(0);
; #pragma unroll
;             for (int j = 0; j < 4; ++j) a = __builtin_amdgcn_mfma_f32_32x32x16_bf16(kfa[j], qf[4 * gq + j], a, 0, 0, 0);
;             if (gq < 2) {
; #pragma unroll
;                 for (int j = 0; j < 4; ++j) kfa[j] = *(const XLAS bf16x8*)(buf + kro + (4 * gq + 8 + j) * 32); }
;             __builtin_amdgcn_sched_barrier(0);
; #pragma unroll
;             for (int j = 0; j < 4; ++j) a = __builtin_amdgcn_mfma_f32_32x32x16_bf16(kfb[j], qf[4 * gq + 4 + j], a, 0, 0, 0);
;         }
;         S[c] = a;
;     }
;     float mx = S[0][0];
; #pragma unroll
;     for (int c = 0; c < 8; ++c)
; #pragma unroll
;         for (int r = 0; r < 16; ++r) mx = __builtin_fmaxf(mx, S[c][r]);
;     mx = __builtin_fmaxf(mx, __shfl_xor(mx, 32));
	v_mfma_f32_32x32x16_bf16 v[98:113], v[146:149], v[182:185], v[98:113]
	global_load_dwordx4 v[146:149], v[212:213], off offset:16
	global_load_dwordx4 v[150:153], v[212:213], off
	v_mfma_f32_32x32x16_bf16 v[98:113], v[220:223], v[178:181], v[98:113]
	ds_read_b128 v[14:17], v0
	ds_read_b128 v[138:141], v0 offset:32
	ds_read_b128 v[142:145], v0 offset:64
	ds_read_b128 v[220:223], v0 offset:96
	ds_read_b128 v[224:227], v0 offset:128
	ds_read_b128 v[232:235], v0 offset:160
	ds_read_b128 v[236:239], v0 offset:192
	ds_read_b128 v[240:243], v0 offset:224
	v_mfma_f32_32x32x16_bf16 v[98:113], v[228:231], v[174:177], v[98:113]
	s_waitcnt lgkmcnt(7)
	v_mfma_f32_32x32x16_bf16 v[114:129], v[14:17], v[2:5], 0
	s_waitcnt lgkmcnt(6)
	v_mfma_f32_32x32x16_bf16 v[114:129], v[138:141], v[170:173], v[114:129]
	s_waitcnt lgkmcnt(5)
	v_mfma_f32_32x32x16_bf16 v[114:129], v[142:145], v[166:169], v[114:129]
	ds_read_b128 v[14:17], v0 offset:352
	ds_read_b128 v[138:141], v0 offset:320
	ds_read_b128 v[142:145], v0 offset:256
	ds_read_b128 v[228:231], v0 offset:288
	s_waitcnt lgkmcnt(8)
	v_mfma_f32_32x32x16_bf16 v[114:129], v[220:223], v[162:165], v[114:129]
	s_waitcnt lgkmcnt(7)
	v_mfma_f32_32x32x16_bf16 v[114:129], v[224:227], v[158:161], v[114:129]
	s_waitcnt lgkmcnt(6)
	v_mfma_f32_32x32x16_bf16 v[114:129], v[232:235], v[154:157], v[114:129]
	s_waitcnt lgkmcnt(5)
	v_mfma_f32_32x32x16_bf16 v[114:129], v[236:239], v[134:137], v[114:129]
	ds_read_b128 v[220:223], v0 offset:384
	ds_read_b128 v[224:227], v0 offset:416
	ds_read_b128 v[232:235], v0 offset:448
	ds_read_b128 v[236:239], v0 offset:480
	s_waitcnt lgkmcnt(8)
	v_mfma_f32_32x32x16_bf16 v[114:129], v[240:243], v[130:133], v[114:129]
	s_waitcnt lgkmcnt(5)
	v_mfma_f32_32x32x16_bf16 v[114:129], v[142:145], v[202:205], v[114:129]
	s_waitcnt lgkmcnt(4)
	v_mfma_f32_32x32x16_bf16 v[114:129], v[228:231], v[198:201], v[114:129]
	v_mfma_f32_32x32x16_bf16 v[114:129], v[138:141], v[194:197], v[114:129]
	v_mfma_f32_32x32x16_bf16 v[114:129], v[14:17], v[190:193], v[114:129]
	s_waitcnt vmcnt(3)
	ds_write_b128 v214, v[6:9] offset:16896
	s_waitcnt vmcnt(2)
	ds_write_b128 v214, v[10:13] offset:16912
	v_add_co_u32_e32 v8, vcc, s45, v212
	s_waitcnt lgkmcnt(0)
	s_nop 0
	v_addc_co_u32_e32 v9, vcc, 0, v213, vcc
	s_barrier
	v_lshl_add_u64 v[6:7], v[212:213], 0, s[22:23]
	global_load_dwordx4 v[142:145], v[8:9], off
	global_load_dwordx4 v[138:141], v[6:7], off offset:16
	v_mfma_f32_32x32x16_bf16 v[114:129], v[220:223], v[186:189], v[114:129]
	v_mfma_f32_32x32x16_bf16 v[114:129], v[224:227], v[182:185], v[114:129]
	v_mfma_f32_32x32x16_bf16 v[114:129], v[232:235], v[178:181], v[114:129]
	ds_read_b128 v[6:9], v0 offset:16896
	ds_read_b128 v[220:223], v0 offset:16928
	ds_read_b128 v[224:227], v0 offset:16960
	ds_read_b128 v[228:231], v0 offset:16992
	ds_read_b128 v[232:235], v0 offset:17024
	ds_read_b128 v[240:243], v0 offset:17056
	ds_read_b128 v[250:253], v0 offset:17088
	ds_read_b128 v[208:211], v0 offset:17120
	v_mfma_f32_32x32x16_bf16 v[114:129], v[236:239], v[174:177], v[114:129]
	s_waitcnt lgkmcnt(7)
	v_mfma_f32_32x32x16_bf16 v[2:17], v[6:9], v[2:5], 0
	s_waitcnt lgkmcnt(6)
	v_mfma_f32_32x32x16_bf16 v[2:17], v[220:223], v[170:173], v[2:17]
	s_waitcnt lgkmcnt(5)
	v_mfma_f32_32x32x16_bf16 v[2:17], v[224:227], v[166:169], v[2:17]
	ds_read_b128 v[166:169], v0 offset:17248
	ds_read_b128 v[170:173], v0 offset:17216
	ds_read_b128 v[220:223], v0 offset:17152
	ds_read_b128 v[224:227], v0 offset:17184
	s_waitcnt lgkmcnt(8)
	v_mfma_f32_32x32x16_bf16 v[2:17], v[228:231], v[162:165], v[2:17]
	s_waitcnt lgkmcnt(7)
	v_mfma_f32_32x32x16_bf16 v[2:17], v[232:235], v[158:161], v[2:17]
	s_waitcnt lgkmcnt(6)
	v_mfma_f32_32x32x16_bf16 v[2:17], v[240:243], v[154:157], v[2:17]
	s_waitcnt lgkmcnt(5)
	v_mfma_f32_32x32x16_bf16 v[2:17], v[250:253], v[134:137], v[2:17]
	ds_read_b128 v[134:137], v0 offset:17280
	ds_read_b128 v[154:157], v0 offset:17312
	ds_read_b128 v[158:161], v0 offset:17344
	ds_read_b128 v[162:165], v0 offset:17376
	s_waitcnt lgkmcnt(8)
	v_mfma_f32_32x32x16_bf16 v[2:17], v[208:211], v[130:133], v[2:17]
	s_waitcnt lgkmcnt(5)
	v_mfma_f32_32x32x16_bf16 v[2:17], v[220:223], v[202:205], v[2:17]
	s_waitcnt lgkmcnt(4)
	v_mfma_f32_32x32x16_bf16 v[2:17], v[224:227], v[198:201], v[2:17]
	v_mfma_f32_32x32x16_bf16 v[2:17], v[170:173], v[194:197], v[2:17]
	v_mfma_f32_32x32x16_bf16 v[2:17], v[166:169], v[190:193], v[2:17]
	v_max_f32_e32 v0, v19, v19
	v_max_f32_e32 v130, v18, v18
	v_max_f32_e32 v0, v130, v0
	v_max3_f32 v0, v0, v20, v21
	v_max3_f32 v0, v0, v22, v23
	v_max3_f32 v0, v0, v24, v25
	v_max3_f32 v0, v0, v26, v27
	v_max3_f32 v0, v0, v28, v29
	v_max3_f32 v0, v0, v30, v31
	v_max3_f32 v0, v0, v32, v33
	v_max3_f32 v0, v0, v34, v35
	v_max3_f32 v0, v0, v36, v37
	v_max3_f32 v0, v0, v38, v39
	v_max3_f32 v0, v0, v40, v41
	v_max3_f32 v0, v0, v42, v43
	v_max3_f32 v0, v0, v44, v45
	v_max3_f32 v0, v0, v46, v47
	v_max3_f32 v0, v0, v48, v49
	v_max3_f32 v0, v0, v50, v51
	v_max3_f32 v0, v0, v52, v53
	v_max3_f32 v0, v0, v54, v55
	v_max3_f32 v0, v0, v56, v57
	v_max3_f32 v0, v0, v58, v59
	v_max3_f32 v0, v0, v60, v61
	v_max3_f32 v0, v0, v62, v63
	v_max3_f32 v0, v0, v64, v65
	s_waitcnt lgkmcnt(3)
	v_mfma_f32_32x32x16_bf16 v[2:17], v[134:137], v[186:189], v[2:17]
	v_max3_f32 v0, v0, v66, v67
	v_max3_f32 v0, v0, v68, v69
	v_max3_f32 v0, v0, v70, v71
	v_max3_f32 v0, v0, v72, v73
	v_max3_f32 v0, v0, v74, v75
	v_max3_f32 v0, v0, v76, v77
	v_max3_f32 v0, v0, v78, v79
	v_max3_f32 v0, v0, v80, v81
	s_waitcnt lgkmcnt(2)
	v_mfma_f32_32x32x16_bf16 v[2:17], v[154:157], v[182:185], v[2:17]
	v_max3_f32 v0, v0, v82, v83
	v_max3_f32 v0, v0, v84, v85
	v_max3_f32 v0, v0, v86, v87
	v_max3_f32 v0, v0, v88, v89
	v_max3_f32 v0, v0, v90, v91
	v_max3_f32 v0, v0, v92, v93
	v_max3_f32 v0, v0, v94, v95
	v_max3_f32 v0, v0, v96, v97
	s_waitcnt lgkmcnt(1)
	v_mfma_f32_32x32x16_bf16 v[2:17], v[158:161], v[178:181], v[2:17]
	v_max3_f32 v0, v0, v98, v99
	v_max3_f32 v0, v0, v100, v101
	v_max3_f32 v0, v0, v102, v103
	v_max3_f32 v0, v0, v104, v105
	v_max3_f32 v0, v0, v106, v107
	v_max3_f32 v0, v0, v108, v109
	v_max3_f32 v0, v0, v110, v111
	v_max3_f32 v0, v0, v112, v113
	s_waitcnt lgkmcnt(0)
	v_mfma_f32_32x32x16_bf16 v[2:17], v[162:165], v[174:177], v[2:17]
	v_max3_f32 v0, v0, v114, v115
	v_max3_f32 v0, v0, v116, v117
	v_max3_f32 v0, v0, v118, v119
	v_max3_f32 v0, v0, v120, v121
	v_max3_f32 v0, v0, v122, v123
	v_max3_f32 v0, v0, v124, v125
	v_max3_f32 v0, v0, v126, v127
	v_max3_f32 v0, v0, v128, v129
	s_nop 3
	v_max3_f32 v0, v0, v2, v3
	v_max3_f32 v0, v0, v4, v5
	v_max3_f32 v0, v0, v6, v7
	v_max3_f32 v0, v0, v8, v9
	v_max3_f32 v0, v0, v10, v11
	v_max3_f32 v0, v0, v12, v13
	v_max3_f32 v0, v0, v14, v15
	v_and_b32_e32 v131, 64, v246
	v_max3_f32 v130, v0, v16, v17
	v_xor_b32_e32 v0, 32, v246
	v_add_u32_e32 v131, 64, v131
	v_cmp_lt_i32_e32 vcc, v0, v131
	s_waitcnt vmcnt(2)
	ds_write_b128 v214, v[150:153]
	ds_write_b128 v214, v[146:149] offset:16
	v_cndmask_b32_e32 v0, v246, v0, vcc
	v_lshlrev_b32_e32 v0, 2, v0
	ds_bpermute_b32 v131, v0, v130
	s_waitcnt lgkmcnt(0)
	s_barrier
; __device__ __forceinline__ unsigned cvtpk(float lo, float hi) { f32x2_t v = {lo, hi}; bf16x2_t b = __builtin_convertvector(v, bf16x2_t); return __builtin_bit_cast(unsigned, b); }
; __device__ __forceinline__ void unit(XLAS unsigned char* lds, const bf16_t* Qg, const bf16_t* Kg, const bf16_t* Vg, bf16_t* Og) {
;     ...
;     float l = 0.f;
;     u32x4 pw[8][2];
; #pragma unroll
;     for (int c = 0; c < 8; ++c) {
;         f32x16 p;
; #pragma unroll
;         for (int r = 0; r < 16; ++r) { p[r] = __builtin_amdgcn_exp2f(S[c][r] - mx); l += p[r]; }
; #pragma unroll
;         for (int s = 0; s < 2; ++s) { pw[c][s].x = cvtpk(p[8 * s + 0], p[8 * s + 1]); pw[c][s].y = cvtpk(p[8 * s + 2], p[8 * s + 3]); pw[c][s].z = cvtpk(p[8 * s + 4], p[8 * s + 5]); pw[c][s].w = cvtpk(p[8 * s + 6], p[8 * s + 7]); }
;     }
	s_add_u32 s48, s48, s0
	v_max_f32_e32 v131, v131, v131
	v_max_f32_e32 v154, v130, v131
	v_sub_f32_e32 v18, v18, v154
	v_sub_f32_e32 v19, v19, v154
	v_exp_f32_e32 v18, v18
	v_exp_f32_e32 v19, v19
	v_sub_f32_e32 v20, v20, v154
	v_exp_f32_e32 v20, v20
	v_sub_f32_e32 v21, v21, v154
	v_exp_f32_e32 v21, v21
	v_sub_f32_e32 v22, v22, v154
	v_exp_f32_e32 v22, v22
	v_sub_f32_e32 v23, v23, v154
	v_cvt_pk_bf16_f32 v130, v18, v19
	v_add_f32_e32 v18, 0, v18
	v_exp_f32_e32 v23, v23
	v_sub_f32_e32 v24, v24, v154
	v_add_f32_e32 v18, v19, v18
	v_exp_f32_e32 v24, v24
	v_sub_f32_e32 v25, v25, v154
	v_add_f32_e32 v18, v20, v18
	v_exp_f32_e32 v25, v25
	v_sub_f32_e32 v26, v26, v154
	v_add_f32_e32 v18, v21, v18
	v_exp_f32_e32 v26, v26
	v_sub_f32_e32 v27, v27, v154
	v_add_f32_e32 v18, v22, v18
	v_exp_f32_e32 v27, v27
	v_sub_f32_e32 v28, v28, v154
	v_add_f32_e32 v18, v23, v18
	v_exp_f32_e32 v28, v28
	v_sub_f32_e32 v29, v29, v154
	v_add_f32_e32 v18, v24, v18
	v_exp_f32_e32 v29, v29
	v_sub_f32_e32 v30, v30, v154
	v_add_f32_e32 v18, v25, v18
	v_exp_f32_e32 v30, v30
	v_sub_f32_e32 v31, v31, v154
	v_add_f32_e32 v18, v26, v18
	v_exp_f32_e32 v31, v31
	v_sub_f32_e32 v32, v32, v154
	v_add_f32_e32 v18, v27, v18
	v_exp_f32_e32 v32, v32
	v_sub_f32_e32 v33, v33, v154
	v_add_f32_e32 v18, v28, v18
	v_exp_f32_e32 v33, v33
	v_add_f32_e32 v18, v29, v18
	v_sub_f32_e32 v19, v34, v154
	v_cvt_pk_bf16_f32 v131, v20, v21
	v_add_f32_e32 v18, v30, v18
	v_exp_f32_e32 v19, v19
	v_sub_f32_e32 v20, v35, v154
	v_add_f32_e32 v18, v31, v18
	v_exp_f32_e32 v20, v20
	v_sub_f32_e32 v21, v36, v154
	v_cvt_pk_bf16_f32 v132, v22, v23
	v_add_f32_e32 v18, v32, v18
	v_exp_f32_e32 v21, v21
	v_sub_f32_e32 v22, v37, v154
	v_add_f32_e32 v18, v33, v18
	v_exp_f32_e32 v22, v22
	v_sub_f32_e32 v23, v38, v154
	v_cvt_pk_bf16_f32 v133, v24, v25
	v_exp_f32_e32 v23, v23
	v_sub_f32_e32 v24, v39, v154
	v_add_f32_e32 v18, v19, v18
	v_exp_f32_e32 v24, v24
	v_sub_f32_e32 v25, v40, v154
	v_add_f32_e32 v18, v20, v18
	v_cvt_pk_bf16_f32 v134, v26, v27
	v_exp_f32_e32 v25, v25
	v_sub_f32_e32 v26, v41, v154
	v_add_f32_e32 v18, v21, v18
	v_exp_f32_e32 v26, v26
	v_sub_f32_e32 v27, v42, v154
	v_add_f32_e32 v18, v22, v18
	v_cvt_pk_bf16_f32 v135, v28, v29
	v_exp_f32_e32 v27, v27
	v_sub_f32_e32 v28, v43, v154
	v_add_f32_e32 v18, v23, v18
	v_exp_f32_e32 v28, v28
	v_sub_f32_e32 v29, v44, v154
	v_add_f32_e32 v18, v24, v18
	v_cvt_pk_bf16_f32 v136, v30, v31
	v_exp_f32_e32 v29, v29
	v_sub_f32_e32 v30, v45, v154
	v_add_f32_e32 v18, v25, v18
	v_exp_f32_e32 v30, v30
	v_sub_f32_e32 v31, v46, v154
	v_add_f32_e32 v18, v26, v18
	v_cvt_pk_bf16_f32 v137, v32, v33
	v_exp_f32_e32 v31, v31
	v_sub_f32_e32 v32, v47, v154
	v_add_f32_e32 v18, v27, v18
	v_exp_f32_e32 v32, v32
	v_sub_f32_e32 v33, v48, v154
	v_add_f32_e32 v18, v28, v18
	v_exp_f32_e32 v33, v33
	v_sub_f32_e32 v34, v49, v154
	v_add_f32_e32 v18, v29, v18
	v_exp_f32_e32 v42, v34
	v_cvt_pk_bf16_f32 v34, v19, v20
	v_add_f32_e32 v18, v30, v18
	v_sub_f32_e32 v19, v50, v154
	v_add_f32_e32 v18, v31, v18
	v_exp_f32_e32 v19, v19
	v_sub_f32_e32 v20, v51, v154
	v_cvt_pk_bf16_f32 v35, v21, v22
	v_add_f32_e32 v18, v32, v18
	v_exp_f32_e32 v20, v20
	v_sub_f32_e32 v21, v52, v154
	v_add_f32_e32 v18, v33, v18
	v_exp_f32_e32 v21, v21
	v_sub_f32_e32 v22, v53, v154
	v_cvt_pk_bf16_f32 v36, v23, v24
	v_add_f32_e32 v18, v42, v18
	v_exp_f32_e32 v22, v22
	v_sub_f32_e32 v23, v54, v154
	v_exp_f32_e32 v23, v23
	v_sub_f32_e32 v24, v55, v154
	v_add_f32_e32 v18, v19, v18
	v_cvt_pk_bf16_f32 v37, v25, v26
	v_exp_f32_e32 v24, v24
	v_sub_f32_e32 v25, v56, v154
	v_add_f32_e32 v18, v20, v18
	v_exp_f32_e32 v25, v25
	v_sub_f32_e32 v26, v57, v154
	v_add_f32_e32 v18, v21, v18
	v_cvt_pk_bf16_f32 v38, v27, v28
	v_exp_f32_e32 v26, v26
	v_sub_f32_e32 v27, v58, v154
	v_add_f32_e32 v18, v22, v18
	v_exp_f32_e32 v27, v27
	v_sub_f32_e32 v28, v59, v154
	v_add_f32_e32 v18, v23, v18
	v_cvt_pk_bf16_f32 v39, v29, v30
	v_exp_f32_e32 v28, v28
	v_sub_f32_e32 v29, v60, v154
	v_add_f32_e32 v18, v24, v18
	v_exp_f32_e32 v29, v29
	v_sub_f32_e32 v30, v61, v154
	v_add_f32_e32 v18, v25, v18
	v_cvt_pk_bf16_f32 v40, v31, v32
	v_exp_f32_e32 v30, v30
	v_sub_f32_e32 v31, v62, v154
	v_add_f32_e32 v18, v26, v18
	v_exp_f32_e32 v31, v31
	v_sub_f32_e32 v32, v63, v154
	v_add_f32_e32 v18, v27, v18
	v_cvt_pk_bf16_f32 v41, v33, v42
	v_exp_f32_e32 v32, v32
	v_sub_f32_e32 v33, v64, v154
	v_add_f32_e32 v18, v28, v18
	v_exp_f32_e32 v33, v33
	v_sub_f32_e32 v42, v65, v154
	v_add_f32_e32 v18, v29, v18
	v_exp_f32_e32 v50, v42
	v_cvt_pk_bf16_f32 v42, v19, v20
	v_add_f32_e32 v18, v30, v18
	v_sub_f32_e32 v19, v66, v154
	v_add_f32_e32 v18, v31, v18
	v_exp_f32_e32 v19, v19
	v_sub_f32_e32 v20, v67, v154
	v_cvt_pk_bf16_f32 v43, v21, v22
	v_add_f32_e32 v18, v32, v18
	v_exp_f32_e32 v20, v20
	v_sub_f32_e32 v21, v68, v154
	v_add_f32_e32 v18, v33, v18
	v_exp_f32_e32 v21, v21
	v_sub_f32_e32 v22, v69, v154
	v_cvt_pk_bf16_f32 v44, v23, v24
	v_add_f32_e32 v18, v50, v18
	v_exp_f32_e32 v22, v22
	v_sub_f32_e32 v23, v70, v154
	v_exp_f32_e32 v23, v23
	v_sub_f32_e32 v24, v71, v154
	v_add_f32_e32 v18, v19, v18
	v_cvt_pk_bf16_f32 v45, v25, v26
	v_exp_f32_e32 v24, v24
	v_sub_f32_e32 v25, v72, v154
	v_add_f32_e32 v18, v20, v18
	v_exp_f32_e32 v25, v25
	v_sub_f32_e32 v26, v73, v154
	v_add_f32_e32 v18, v21, v18
	v_cvt_pk_bf16_f32 v46, v27, v28
	v_exp_f32_e32 v26, v26
	v_sub_f32_e32 v27, v74, v154
	v_add_f32_e32 v18, v22, v18
	v_exp_f32_e32 v27, v27
	v_sub_f32_e32 v28, v75, v154
	v_add_f32_e32 v18, v23, v18
	v_cvt_pk_bf16_f32 v47, v29, v30
	v_exp_f32_e32 v28, v28
	v_sub_f32_e32 v29, v76, v154
	v_add_f32_e32 v18, v24, v18
	v_exp_f32_e32 v29, v29
	v_sub_f32_e32 v30, v77, v154
	v_add_f32_e32 v18, v25, v18
; #define XLAS __attribute__((address_space(3)))
; __device__ __forceinline__ unsigned cvtpk(float lo, float hi) { f32x2_t v = {lo, hi}; bf16x2_t b = __builtin_convertvector(v, bf16x2_t); return __builtin_bit_cast(unsigned, b); }
; __device__ __forceinline__ void unit(XLAS unsigned char* lds, const bf16_t* Qg, const bf16_t* Kg, const bf16_t* Vg, bf16_t* Og) {
;     ...
; #pragma unroll
;     for (int c = 0; c < 8; ++c) {
;         f32x16 p;
; #pragma unroll
;         for (int r = 0; r < 16; ++r) { p[r] = __builtin_amdgcn_exp2f(S[c][r] - mx); l += p[r]; }
; #pragma unroll
;         for (int s = 0; s < 2; ++s) { pw[c][s].x = cvtpk(p[8 * s + 0], p[8 * s + 1]); pw[c][s].y = cvtpk(p[8 * s + 2], p[8 * s + 3]); pw[c][s].z = cvtpk(p[8 * s + 4], p[8 * s + 5]); pw[c][s].w = cvtpk(p[8 * s + 6], p[8 * s + 7]); }
;     }
;     l += __shfl_xor(l, 32);
;     const float rl = 1.0f / l;
;     bf16_t* obase = Og + (size_t)(wid * 32 + (lane >> 3)) * 1024 + (lane & 7) * 8;
; #pragma unroll
;     for (int db = 0; db < 8; ++db) {
;         XLAS unsigned char* buf = lds + (db & 1) * CHB;
;         *(XLAS u32x4*)(buf + wofs) = g[db & 1][0]; *(XLAS u32x4*)(buf + wofs + 16) = g[db & 1][1];
;         __syncthreads();
;         if (db < 6) { g[db & 1][0] = *(const u32x4*)(XAT_SRC(db + 10)); g[db & 1][1] = *(const u32x4*)(XAT_SRC(db + 10) + 8); }
;         f32x16 o = {};
; #pragma unroll
;         for (int kb = 0; kb < 8; ++kb)
; #pragma unroll
;             for (int s = 0; s < 2; ++s) { const bf16x8 vf = *(const XLAS bf16x8*)(buf + vro + kb * 64 + s * 32); o = __builtin_amdgcn_mfma_f32_32x32x16_bf16(vf, __builtin_bit_cast(bf16x8, pw[kb][s]), o, 0, 0, 0); }
	v_cvt_pk_bf16_f32 v48, v31, v32
	v_exp_f32_e32 v30, v30
	v_sub_f32_e32 v31, v78, v154
	v_add_f32_e32 v18, v26, v18
	v_exp_f32_e32 v31, v31
	v_sub_f32_e32 v32, v79, v154
	v_add_f32_e32 v18, v27, v18
	v_cvt_pk_bf16_f32 v49, v33, v50
	v_exp_f32_e32 v32, v32
	v_sub_f32_e32 v33, v80, v154
	v_add_f32_e32 v18, v28, v18
	v_exp_f32_e32 v33, v33
	v_sub_f32_e32 v50, v81, v154
	v_add_f32_e32 v18, v29, v18
	v_exp_f32_e32 v58, v50
	v_cvt_pk_bf16_f32 v50, v19, v20
	v_add_f32_e32 v18, v30, v18
	v_sub_f32_e32 v19, v82, v154
	v_add_f32_e32 v18, v31, v18
	v_exp_f32_e32 v19, v19
	v_sub_f32_e32 v20, v83, v154
	v_cvt_pk_bf16_f32 v51, v21, v22
	v_add_f32_e32 v18, v32, v18
	v_exp_f32_e32 v20, v20
	v_sub_f32_e32 v21, v84, v154
	v_add_f32_e32 v18, v33, v18
	v_exp_f32_e32 v21, v21
	v_sub_f32_e32 v22, v85, v154
	v_cvt_pk_bf16_f32 v52, v23, v24
	v_add_f32_e32 v18, v58, v18
	v_exp_f32_e32 v22, v22
	v_sub_f32_e32 v23, v86, v154
	v_exp_f32_e32 v23, v23
	v_sub_f32_e32 v24, v87, v154
	v_add_f32_e32 v18, v19, v18
	v_cvt_pk_bf16_f32 v53, v25, v26
	v_exp_f32_e32 v24, v24
	v_sub_f32_e32 v25, v88, v154
	v_add_f32_e32 v18, v20, v18
	v_exp_f32_e32 v25, v25
	v_sub_f32_e32 v26, v89, v154
	v_add_f32_e32 v18, v21, v18
	v_cvt_pk_bf16_f32 v54, v27, v28
	v_exp_f32_e32 v26, v26
	v_sub_f32_e32 v27, v90, v154
	v_add_f32_e32 v18, v22, v18
	v_exp_f32_e32 v27, v27
	v_sub_f32_e32 v28, v91, v154
	v_add_f32_e32 v18, v23, v18
	v_cvt_pk_bf16_f32 v55, v29, v30
	v_exp_f32_e32 v28, v28
	v_sub_f32_e32 v29, v92, v154
	v_add_f32_e32 v18, v24, v18
	v_exp_f32_e32 v29, v29
	v_sub_f32_e32 v30, v93, v154
	v_add_f32_e32 v18, v25, v18
	v_cvt_pk_bf16_f32 v56, v31, v32
	v_exp_f32_e32 v30, v30
	v_sub_f32_e32 v31, v94, v154
	v_add_f32_e32 v18, v26, v18
	v_exp_f32_e32 v31, v31
	v_sub_f32_e32 v32, v95, v154
	v_add_f32_e32 v18, v27, v18
	v_cvt_pk_bf16_f32 v57, v33, v58
	v_exp_f32_e32 v32, v32
	v_sub_f32_e32 v33, v96, v154
	v_add_f32_e32 v18, v28, v18
	v_exp_f32_e32 v33, v33
	v_sub_f32_e32 v58, v97, v154
	v_add_f32_e32 v18, v29, v18
	v_exp_f32_e32 v66, v58
	v_cvt_pk_bf16_f32 v58, v19, v20
	v_add_f32_e32 v18, v30, v18
	v_sub_f32_e32 v19, v98, v154
	v_add_f32_e32 v18, v31, v18
	v_exp_f32_e32 v19, v19
	v_sub_f32_e32 v20, v99, v154
	v_cvt_pk_bf16_f32 v59, v21, v22
	v_add_f32_e32 v18, v32, v18
	v_exp_f32_e32 v20, v20
	v_sub_f32_e32 v21, v100, v154
	v_add_f32_e32 v18, v33, v18
	v_exp_f32_e32 v21, v21
	v_sub_f32_e32 v22, v101, v154
	v_cvt_pk_bf16_f32 v60, v23, v24
	v_add_f32_e32 v18, v66, v18
	v_exp_f32_e32 v22, v22
	v_sub_f32_e32 v23, v102, v154
	v_exp_f32_e32 v23, v23
	v_sub_f32_e32 v24, v103, v154
	v_add_f32_e32 v18, v19, v18
	v_cvt_pk_bf16_f32 v61, v25, v26
	v_exp_f32_e32 v24, v24
	v_sub_f32_e32 v25, v104, v154
	v_add_f32_e32 v18, v20, v18
	v_exp_f32_e32 v25, v25
	v_sub_f32_e32 v26, v105, v154
	v_add_f32_e32 v18, v21, v18
	v_cvt_pk_bf16_f32 v62, v27, v28
	v_exp_f32_e32 v26, v26
	v_sub_f32_e32 v27, v106, v154
	v_add_f32_e32 v18, v22, v18
	v_exp_f32_e32 v27, v27
	v_sub_f32_e32 v28, v107, v154
	v_add_f32_e32 v18, v23, v18
	v_cvt_pk_bf16_f32 v63, v29, v30
	v_exp_f32_e32 v28, v28
	v_sub_f32_e32 v29, v108, v154
	v_add_f32_e32 v18, v24, v18
	v_exp_f32_e32 v29, v29
	v_sub_f32_e32 v30, v109, v154
	v_add_f32_e32 v18, v25, v18
	v_cvt_pk_bf16_f32 v64, v31, v32
	v_exp_f32_e32 v30, v30
	v_sub_f32_e32 v31, v110, v154
	v_add_f32_e32 v18, v26, v18
	v_exp_f32_e32 v31, v31
	v_sub_f32_e32 v32, v111, v154
	v_add_f32_e32 v18, v27, v18
	v_cvt_pk_bf16_f32 v65, v33, v66
	v_exp_f32_e32 v32, v32
	v_sub_f32_e32 v33, v112, v154
	v_add_f32_e32 v18, v28, v18
	v_exp_f32_e32 v33, v33
	v_sub_f32_e32 v66, v113, v154
	v_add_f32_e32 v18, v29, v18
	v_exp_f32_e32 v74, v66
	v_add_f32_e32 v18, v30, v18
	v_add_f32_e32 v18, v31, v18
	v_add_f32_e32 v18, v32, v18
	v_add_f32_e32 v18, v33, v18
	v_cvt_pk_bf16_f32 v67, v21, v22
	v_add_f32_e32 v22, v74, v18
	v_sub_f32_e32 v18, v114, v154
	v_cvt_pk_bf16_f32 v68, v23, v24
	v_exp_f32_e32 v23, v18
	v_sub_f32_e32 v18, v115, v154
	v_exp_f32_e32 v24, v18
	v_sub_f32_e32 v18, v116, v154
	v_cvt_pk_bf16_f32 v69, v25, v26
	v_exp_f32_e32 v25, v18
	v_sub_f32_e32 v18, v117, v154
	v_exp_f32_e32 v26, v18
	v_sub_f32_e32 v18, v118, v154
	v_cvt_pk_bf16_f32 v70, v27, v28
	v_exp_f32_e32 v27, v18
	v_sub_f32_e32 v18, v119, v154
	v_exp_f32_e32 v28, v18
	v_sub_f32_e32 v18, v120, v154
	v_cvt_pk_bf16_f32 v71, v29, v30
	v_exp_f32_e32 v29, v18
	v_sub_f32_e32 v18, v121, v154
	v_exp_f32_e32 v85, v18
	v_sub_f32_e32 v18, v122, v154
	v_exp_f32_e32 v90, v18
	v_sub_f32_e32 v18, v123, v154
	v_exp_f32_e32 v91, v18
	v_sub_f32_e32 v18, v124, v154
	v_exp_f32_e32 v92, v18
	v_sub_f32_e32 v18, v125, v154
	v_exp_f32_e32 v93, v18
	v_sub_f32_e32 v18, v126, v154
	v_exp_f32_e32 v94, v18
	v_sub_f32_e32 v18, v127, v154
	v_exp_f32_e32 v82, v18
	v_sub_f32_e32 v18, v128, v154
	v_exp_f32_e32 v83, v18
	v_sub_f32_e32 v18, v129, v154
	v_exp_f32_e32 v84, v18
	v_mul_u32_u24_e32 v18, 0x210, v216
	v_add3_u32 v99, 0, v18, v218
	v_cvt_pk_bf16_f32 v66, v19, v20
	ds_read_b128 v[18:21], v99
	ds_read_b128 v[86:89], v99 offset:32
	v_add_f32_e32 v22, v23, v22
	v_add_f32_e32 v22, v24, v22
	v_add_f32_e32 v22, v25, v22
	v_add_f32_e32 v22, v26, v22
	v_add_f32_e32 v22, v27, v22
	v_add_f32_e32 v22, v28, v22
	v_cvt_pk_bf16_f32 v72, v31, v32
	v_cvt_pk_bf16_f32 v73, v33, v74
	v_cvt_pk_bf16_f32 v74, v23, v24
	v_cvt_pk_bf16_f32 v75, v25, v26
	v_cvt_pk_bf16_f32 v76, v27, v28
	v_cvt_pk_bf16_f32 v77, v29, v85
	v_add_f32_e32 v95, v29, v22
	s_waitcnt lgkmcnt(1)
	v_mfma_f32_32x32x16_bf16 v[18:33], v[18:21], v[130:133], 0
	v_add_f32_e32 v85, v85, v95
	v_add_f32_e32 v85, v90, v85
	v_add_f32_e32 v85, v91, v85
	v_add_f32_e32 v85, v92, v85
	v_cvt_pk_bf16_f32 v78, v90, v91
	v_cvt_pk_bf16_f32 v79, v92, v93
	v_add_f32_e32 v85, v93, v85
	ds_read_b128 v[90:93], v99 offset:64
	s_waitcnt lgkmcnt(1)
; #define XLAS __attribute__((address_space(3)))
; __device__ __forceinline__ unsigned cvtpk(float lo, float hi) { f32x2_t v = {lo, hi}; bf16x2_t b = __builtin_convertvector(v, bf16x2_t); return __builtin_bit_cast(unsigned, b); }
; __device__ __forceinline__ void unit(XLAS unsigned char* lds, const bf16_t* Qg, const bf16_t* Kg, const bf16_t* Vg, bf16_t* Og) {
;     ...
;         for (int r = 0; r < 16; ++r) { p[r] = __builtin_amdgcn_exp2f(S[c][r] - mx); l += p[r]; }
; #pragma unroll
;         for (int s = 0; s < 2; ++s) { pw[c][s].x = cvtpk(p[8 * s + 0], p[8 * s + 1]); pw[c][s].y = cvtpk(p[8 * s + 2], p[8 * s + 3]); pw[c][s].z = cvtpk(p[8 * s + 4], p[8 * s + 5]); pw[c][s].w = cvtpk(p[8 * s + 6], p[8 * s + 7]); }
;     }
;     l += __shfl_xor(l, 32);
;     const float rl = 1.0f / l;
;     bf16_t* obase = Og + (size_t)(wid * 32 + (lane >> 3)) * 1024 + (lane & 7) * 8;
; #pragma unroll
;     for (int db = 0; db < 8; ++db) {
;         XLAS unsigned char* buf = lds + (db & 1) * CHB;
;         *(XLAS u32x4*)(buf + wofs) = g[db & 1][0]; *(XLAS u32x4*)(buf + wofs + 16) = g[db & 1][1];
;         __syncthreads();
;         if (db < 6) { g[db & 1][0] = *(const u32x4*)(XAT_SRC(db + 10)); g[db & 1][1] = *(const u32x4*)(XAT_SRC(db + 10) + 8); }
;         f32x16 o = {};
; #pragma unroll
;         for (int kb = 0; kb < 8; ++kb)
; #pragma unroll
;             for (int s = 0; s < 2; ++s) { const bf16x8 vf = *(const XLAS bf16x8*)(buf + vro + kb * 64 + s * 32); o = __builtin_amdgcn_mfma_f32_32x32x16_bf16(vf, __builtin_bit_cast(bf16x8, pw[kb][s]), o, 0, 0, 0); }
; #pragma unroll
;         for (int g4 = 0; g4 < 4; ++g4) { u32x2 w; w.x = cvtpk(o[4 * g4] * rl, o[4 * g4 + 1] * rl); w.y = cvtpk(o[4 * g4 + 2] * rl, o[4 * g4 + 3] * rl);
;             *(XLAS u32x2*)(xs + r32 * 144 + ((db & 1) * 32 + 8 * g4 + 4 * hi) * 2) = w; }
	v_mfma_f32_32x32x16_bf16 v[18:33], v[86:89], v[134:137], v[18:33]
	v_add_f32_e32 v85, v94, v85
	v_cvt_pk_bf16_f32 v80, v94, v82
	v_add_f32_e32 v82, v82, v85
	v_add_f32_e32 v82, v83, v82
	v_cvt_pk_bf16_f32 v81, v83, v84
	v_add_f32_e32 v88, v84, v82
	ds_read_b128 v[82:85], v99 offset:96
	s_waitcnt lgkmcnt(1)
	v_mfma_f32_32x32x16_bf16 v[18:33], v[90:93], v[34:37], v[18:33]
	v_sub_f32_e32 v2, v2, v154
	v_exp_f32_e32 v89, v2
	v_sub_f32_e32 v2, v3, v154
	v_exp_f32_e32 v90, v2
	v_sub_f32_e32 v2, v4, v154
	v_exp_f32_e32 v91, v2
	v_sub_f32_e32 v2, v5, v154
	v_exp_f32_e32 v92, v2
	ds_read_b128 v[2:5], v99 offset:128
	s_waitcnt lgkmcnt(1)
	v_mfma_f32_32x32x16_bf16 v[18:33], v[82:85], v[38:41], v[18:33]
	v_sub_f32_e32 v6, v6, v154
	v_exp_f32_e32 v82, v6
	v_sub_f32_e32 v6, v7, v154
	v_exp_f32_e32 v83, v6
	v_sub_f32_e32 v6, v8, v154
	v_exp_f32_e32 v84, v6
	v_sub_f32_e32 v85, v9, v154
	ds_read_b128 v[6:9], v99 offset:160
	s_waitcnt lgkmcnt(1)
	v_mfma_f32_32x32x16_bf16 v[18:33], v[2:5], v[42:45], v[18:33]
	v_sub_f32_e32 v2, v10, v154
	v_exp_f32_e32 v10, v2
	v_sub_f32_e32 v2, v11, v154
	v_exp_f32_e32 v11, v2
	ds_read_b128 v[2:5], v99 offset:192
	v_exp_f32_e32 v85, v85
	v_sub_f32_e32 v12, v12, v154
	s_waitcnt lgkmcnt(1)
	v_mfma_f32_32x32x16_bf16 v[18:33], v[6:9], v[46:49], v[18:33]
	v_sub_f32_e32 v6, v13, v154
	v_exp_f32_e32 v13, v6
	v_sub_f32_e32 v6, v14, v154
	v_exp_f32_e32 v14, v6
	ds_read_b128 v[6:9], v99 offset:224
	v_exp_f32_e32 v12, v12
	v_sub_f32_e32 v15, v15, v154
	s_waitcnt lgkmcnt(1)
	v_mfma_f32_32x32x16_bf16 v[18:33], v[2:5], v[50:53], v[18:33]
	v_sub_f32_e32 v2, v16, v154
	v_exp_f32_e32 v16, v2
	v_sub_f32_e32 v2, v17, v154
	v_exp_f32_e32 v17, v2
	ds_read_b128 v[2:5], v99 offset:256
	v_exp_f32_e32 v15, v15
	v_cvt_pk_bf16_f32 v86, v89, v90
	s_waitcnt lgkmcnt(1)
	v_mfma_f32_32x32x16_bf16 v[18:33], v[6:9], v[54:57], v[18:33]
	v_add_f32_e32 v6, v89, v88
	v_add_f32_e32 v6, v90, v6
	v_add_f32_e32 v6, v91, v6
	v_add_f32_e32 v6, v92, v6
	v_add_f32_e32 v88, v82, v6
	ds_read_b128 v[6:9], v99 offset:288
	v_cvt_pk_bf16_f32 v87, v91, v92
	s_waitcnt lgkmcnt(1)
	v_mfma_f32_32x32x16_bf16 v[18:33], v[2:5], v[58:61], v[18:33]
	v_add_f32_e32 v2, v83, v88
	v_add_f32_e32 v2, v84, v2
	v_add_f32_e32 v2, v85, v2
	v_add_f32_e32 v2, v10, v2
	v_add_f32_e32 v2, v11, v2
	v_add_f32_e32 v88, v12, v2
	ds_read_b128 v[2:5], v99 offset:320
	s_waitcnt lgkmcnt(1)
	v_mfma_f32_32x32x16_bf16 v[18:33], v[6:9], v[62:65], v[18:33]
	v_add_f32_e32 v6, v13, v88
	v_add_f32_e32 v6, v14, v6
	v_add_f32_e32 v6, v15, v6
	v_add_f32_e32 v6, v16, v6
	v_add_f32_e32 v90, v17, v6
	ds_read_b128 v[6:9], v99 offset:352
	ds_bpermute_b32 v0, v0, v90
	s_waitcnt lgkmcnt(2)
	v_mfma_f32_32x32x16_bf16 v[18:33], v[2:5], v[66:69], v[18:33]
	ds_read_b128 v[2:5], v99 offset:384
	v_cvt_pk_bf16_f32 v88, v82, v83
	v_cvt_pk_bf16_f32 v82, v10, v11
	s_waitcnt lgkmcnt(1)
	v_add_f32_e32 v0, v90, v0
	v_div_scale_f32 v10, s[8:9], v0, v0, 1.0
	v_rcp_f32_e32 v11, v10
	v_mfma_f32_32x32x16_bf16 v[18:33], v[6:9], v[70:73], v[18:33]
	v_cvt_pk_bf16_f32 v83, v12, v13
	v_cvt_pk_bf16_f32 v89, v84, v85
	v_fma_f32 v6, -v10, v11, 1.0
	v_fmac_f32_e32 v11, v6, v11
	ds_read_b128 v[6:9], v99 offset:416
	v_cvt_pk_bf16_f32 v84, v14, v15
	v_cvt_pk_bf16_f32 v85, v16, v17
	s_waitcnt lgkmcnt(1)
	v_mfma_f32_32x32x16_bf16 v[18:33], v[2:5], v[74:77], v[18:33]
	v_div_scale_f32 v2, vcc, 1.0, v0, 1.0
	v_mul_f32_e32 v12, v2, v11
	v_fma_f32 v3, -v10, v12, v2
	v_fmac_f32_e32 v12, v3, v11
	v_fma_f32 v10, -v10, v12, v2
	ds_read_b128 v[2:5], v99 offset:448
	s_waitcnt lgkmcnt(1)
	v_mfma_f32_32x32x16_bf16 v[18:33], v[6:9], v[78:81], v[18:33]
	v_div_fmas_f32 v6, v10, v11, v12
	v_div_fixup_f32 v98, v6, v0, 1.0
	v_mul_u32_u24_e32 v0, 0x90, v216
	v_lshlrev_b32_e32 v6, 3, v217
	v_add3_u32 v0, s16, v0, v6
	ds_read_b128 v[6:9], v99 offset:480
	v_add_u32_e32 v100, 0x8800, v0
	s_waitcnt lgkmcnt(1)
	v_mfma_f32_32x32x16_bf16 v[18:33], v[2:5], v[86:89], v[18:33]
	v_add_co_u32_e32 v4, vcc, s46, v212
	v_lshl_add_u64 v[2:3], v[212:213], 0, s[34:35]
	s_nop 0
	v_addc_co_u32_e32 v5, vcc, 0, v213, vcc
	global_load_dwordx4 v[94:97], v[4:5], off
	global_load_dwordx4 v[90:93], v[2:3], off offset:16
	v_lshlrev_b32_e32 v0, 4, v215
	s_waitcnt lgkmcnt(0)
	v_mfma_f32_32x32x16_bf16 v[18:33], v[6:9], v[82:85], v[18:33]
	v_and_b32_e32 v0, 0x70, v0
	s_addc_u32 s49, s49, s15
	s_nop 9
	v_pk_mul_f32 v[2:3], v[18:19], v[98:99] op_sel_hi:[1,0]
	v_pk_mul_f32 v[4:5], v[20:21], v[98:99] op_sel_hi:[1,0]
	v_cvt_pk_bf16_f32 v2, v2, v3
	v_cvt_pk_bf16_f32 v3, v4, v5
	v_pk_mul_f32 v[4:5], v[22:23], v[98:99] op_sel_hi:[1,0]
	v_pk_mul_f32 v[6:7], v[24:25], v[98:99] op_sel_hi:[1,0]
	v_cvt_pk_bf16_f32 v4, v4, v5
	v_cvt_pk_bf16_f32 v5, v6, v7
	ds_write2_b64 v100, v[2:3], v[4:5] offset1:2
	v_pk_mul_f32 v[2:3], v[26:27], v[98:99] op_sel_hi:[1,0]
	v_pk_mul_f32 v[4:5], v[28:29], v[98:99] op_sel_hi:[1,0]
	v_cvt_pk_bf16_f32 v2, v2, v3
	v_cvt_pk_bf16_f32 v3, v4, v5
	v_pk_mul_f32 v[4:5], v[30:31], v[98:99] op_sel_hi:[1,0]
	v_pk_mul_f32 v[6:7], v[32:33], v[98:99] op_sel_hi:[1,0]
	v_cvt_pk_bf16_f32 v4, v4, v5
	v_cvt_pk_bf16_f32 v5, v6, v7
	ds_write2_b64 v100, v[2:3], v[4:5] offset0:4 offset1:6
	s_waitcnt vmcnt(3)
	ds_write_b128 v214, v[142:145] offset:16896
	s_waitcnt vmcnt(2)
	ds_write_b128 v214, v[138:141] offset:16912
	s_waitcnt lgkmcnt(0)
	s_barrier
; #define XLAS __attribute__((address_space(3)))
; __device__ __forceinline__ unsigned cvtpk(float lo, float hi) { f32x2_t v = {lo, hi}; bf16x2_t b = __builtin_convertvector(v, bf16x2_t); return __builtin_bit_cast(unsigned, b); }
; __device__ __forceinline__ void unit(XLAS unsigned char* lds, const bf16_t* Qg, const bf16_t* Kg, const bf16_t* Vg, bf16_t* Og) {
;     ...
;     for (int db = 0; db < 8; ++db) {
;         XLAS unsigned char* buf = lds + (db & 1) * CHB;
;         *(XLAS u32x4*)(buf + wofs) = g[db & 1][0]; *(XLAS u32x4*)(buf + wofs + 16) = g[db & 1][1];
;         __syncthreads();
;         if (db < 6) { g[db & 1][0] = *(const u32x4*)(XAT_SRC(db + 10)); g[db & 1][1] = *(const u32x4*)(XAT_SRC(db + 10) + 8); }
;         f32x16 o = {};
; #pragma unroll
;         for (int kb = 0; kb < 8; ++kb)
; #pragma unroll
;             for (int s = 0; s < 2; ++s) { const bf16x8 vf = *(const XLAS bf16x8*)(buf + vro + kb * 64 + s * 32); o = __builtin_amdgcn_mfma_f32_32x32x16_bf16(vf, __builtin_bit_cast(bf16x8, pw[kb][s]), o, 0, 0, 0); }
; #pragma unroll
;         for (int g4 = 0; g4 < 4; ++g4) { u32x2 w; w.x = cvtpk(o[4 * g4] * rl, o[4 * g4 + 1] * rl); w.y = cvtpk(o[4 * g4 + 2] * rl, o[4 * g4 + 3] * rl);
;             *(XLAS u32x2*)(xs + r32 * 144 + ((db & 1) * 32 + 8 * g4 + 4 * hi) * 2) = w; }
;         if (db & 1) {
; #pragma unroll
;             for (int i = 0; i < 4; ++i) { const u32x4 v = *(const XLAS u32x4*)(xs + (8 * i + (lane >> 3)) * 144 + (lane & 7) * 16); *(u32x4*)(obase + (size_t)(8 * i) * 1024 + (db >> 1) * 64) = v; }
;         }
	ds_read_b128 v[140:143], v99 offset:16896
	ds_read_b128 v[144:147], v99 offset:16928
	ds_read_b128 v[148:151], v99 offset:16960
	ds_read_b128 v[152:155], v99 offset:16992
	ds_read_b128 v[156:159], v99 offset:17024
	ds_read_b128 v[160:163], v99 offset:17056
	ds_read_b128 v[164:167], v99 offset:17088
	ds_read_b128 v[168:171], v99 offset:17120
	s_waitcnt lgkmcnt(7)
	v_mfma_f32_32x32x16_bf16 v[2:17], v[140:143], v[130:133], 0
	ds_read_b128 v[140:143], v99 offset:17152
	v_bfe_u32 v28, v215, 3, 3
	v_or_b32_e32 v26, s26, v28
	v_ashrrev_i32_e32 v27, 31, v26
	s_waitcnt lgkmcnt(7)
	v_mfma_f32_32x32x16_bf16 v[2:17], v[144:147], v[134:137], v[2:17]
	ds_read_b128 v[144:147], v99 offset:17184
	s_waitcnt lgkmcnt(7)
	v_mfma_f32_32x32x16_bf16 v[2:17], v[148:151], v[34:37], v[2:17]
	ds_read_b128 v[148:151], v99 offset:17216
	s_waitcnt lgkmcnt(7)
	v_mfma_f32_32x32x16_bf16 v[2:17], v[152:155], v[38:41], v[2:17]
	ds_read_b128 v[152:155], v99 offset:17248
	s_waitcnt lgkmcnt(7)
	v_mfma_f32_32x32x16_bf16 v[2:17], v[156:159], v[42:45], v[2:17]
	ds_read_b128 v[156:159], v99 offset:17280
	s_waitcnt lgkmcnt(7)
	v_mfma_f32_32x32x16_bf16 v[2:17], v[160:163], v[46:49], v[2:17]
	ds_read_b128 v[160:163], v99 offset:17312
	s_waitcnt lgkmcnt(7)
	v_mfma_f32_32x32x16_bf16 v[2:17], v[164:167], v[50:53], v[2:17]
	ds_read_b128 v[164:167], v99 offset:17344
	s_waitcnt lgkmcnt(7)
	v_mfma_f32_32x32x16_bf16 v[2:17], v[168:171], v[54:57], v[2:17]
	ds_read_b128 v[168:171], v99 offset:17376
	s_waitcnt lgkmcnt(7)
	v_mfma_f32_32x32x16_bf16 v[2:17], v[140:143], v[58:61], v[2:17]
	s_waitcnt lgkmcnt(6)
	v_mfma_f32_32x32x16_bf16 v[2:17], v[144:147], v[62:65], v[2:17]
	s_waitcnt lgkmcnt(5)
	v_mfma_f32_32x32x16_bf16 v[2:17], v[148:151], v[66:69], v[2:17]
	s_waitcnt lgkmcnt(4)
	v_mfma_f32_32x32x16_bf16 v[2:17], v[152:155], v[70:73], v[2:17]
	s_waitcnt lgkmcnt(3)
	v_mfma_f32_32x32x16_bf16 v[2:17], v[156:159], v[74:77], v[2:17]
	s_waitcnt lgkmcnt(2)
	v_mfma_f32_32x32x16_bf16 v[2:17], v[160:163], v[78:81], v[2:17]
	s_waitcnt lgkmcnt(1)
	v_mfma_f32_32x32x16_bf16 v[2:17], v[164:167], v[86:89], v[2:17]
	v_lshlrev_b64 v[18:19], 11, v[26:27]
	v_lshl_add_u64 v[18:19], s[4:5], 0, v[18:19]
	v_lshl_add_u64 v[26:27], v[18:19], 0, v[0:1]
	v_lshl_add_u64 v[18:19], v[212:213], 0, s[36:37]
	s_mov_b64 s[4:5], 0
	s_waitcnt lgkmcnt(0)
	v_mfma_f32_32x32x16_bf16 v[2:17], v[168:171], v[82:85], v[2:17]
	s_nop 11
	v_pk_mul_f32 v[2:3], v[2:3], v[98:99] op_sel_hi:[1,0]
	v_pk_mul_f32 v[4:5], v[4:5], v[98:99] op_sel_hi:[1,0]
	v_cvt_pk_bf16_f32 v2, v2, v3
	v_cvt_pk_bf16_f32 v3, v4, v5
	v_pk_mul_f32 v[4:5], v[6:7], v[98:99] op_sel_hi:[1,0]
	v_pk_mul_f32 v[6:7], v[8:9], v[98:99] op_sel_hi:[1,0]
	v_cvt_pk_bf16_f32 v4, v4, v5
	v_cvt_pk_bf16_f32 v5, v6, v7
	ds_write2_b64 v100, v[2:3], v[4:5] offset0:8 offset1:10
	v_pk_mul_f32 v[2:3], v[10:11], v[98:99] op_sel_hi:[1,0]
	v_pk_mul_f32 v[4:5], v[12:13], v[98:99] op_sel_hi:[1,0]
	v_cvt_pk_bf16_f32 v2, v2, v3
	v_cvt_pk_bf16_f32 v3, v4, v5
	v_pk_mul_f32 v[4:5], v[14:15], v[98:99] op_sel_hi:[1,0]
	v_pk_mul_f32 v[6:7], v[16:17], v[98:99] op_sel_hi:[1,0]
	v_cvt_pk_bf16_f32 v4, v4, v5
	v_cvt_pk_bf16_f32 v5, v6, v7
	ds_write2_b64 v100, v[2:3], v[4:5] offset0:12 offset1:14
	v_mul_u32_u24_e32 v2, 0x90, v28
	v_add_co_u32_e32 v6, vcc, s47, v212
	v_add3_u32 v0, s16, v0, v2
	s_nop 0
	v_addc_co_u32_e32 v7, vcc, 0, v213, vcc
	ds_read_b128 v[2:5], v0 offset:34816
	global_load_dwordx4 v[102:105], v[6:7], off
	global_load_dwordx4 v[106:109], v[18:19], off offset:16
	ds_read_b128 v[6:9], v0 offset:35968
	v_add_co_u32_e32 v28, vcc, s28, v26
	s_waitcnt lgkmcnt(1)
	global_store_dwordx4 v[26:27], v[2:5], off
	v_addc_co_u32_e32 v29, vcc, 0, v27, vcc
	ds_read_b128 v[2:5], v0 offset:37120
	s_waitcnt lgkmcnt(1)
	global_store_dwordx4 v[28:29], v[6:9], off
	ds_read_b128 v[6:9], v0 offset:38272
	v_add_co_u32_e32 v30, vcc, s29, v26
	s_nop 1
	v_addc_co_u32_e32 v31, vcc, 0, v27, vcc
	v_add_co_u32_e32 v32, vcc, s42, v26
	s_waitcnt lgkmcnt(1)
	global_store_dwordx4 v[30:31], v[2:5], off
	v_addc_co_u32_e32 v33, vcc, 0, v27, vcc
	s_waitcnt lgkmcnt(0)
	global_store_dwordx4 v[32:33], v[6:9], off
	s_waitcnt vmcnt(7)
	ds_write_b128 v214, v[94:97]
	s_waitcnt vmcnt(6)
	ds_write_b128 v214, v[90:93] offset:16
	s_waitcnt lgkmcnt(0)
	s_barrier
; #define XLAS __attribute__((address_space(3)))
; __device__ __forceinline__ unsigned cvtpk(float lo, float hi) { f32x2_t v = {lo, hi}; bf16x2_t b = __builtin_convertvector(v, bf16x2_t); return __builtin_bit_cast(unsigned, b); }
; __device__ __forceinline__ void unit(XLAS unsigned char* lds, const bf16_t* Qg, const bf16_t* Kg, const bf16_t* Vg, bf16_t* Og) {
;     ...
;     for (int db = 0; db < 8; ++db) {
;         XLAS unsigned char* buf = lds + (db & 1) * CHB;
;         *(XLAS u32x4*)(buf + wofs) = g[db & 1][0]; *(XLAS u32x4*)(buf + wofs + 16) = g[db & 1][1];
;         __syncthreads();
;         if (db < 6) { g[db & 1][0] = *(const u32x4*)(XAT_SRC(db + 10)); g[db & 1][1] = *(const u32x4*)(XAT_SRC(db + 10) + 8); }
;         f32x16 o = {};
; #pragma unroll
;         for (int kb = 0; kb < 8; ++kb)
; #pragma unroll
;             for (int s = 0; s < 2; ++s) { const bf16x8 vf = *(const XLAS bf16x8*)(buf + vro + kb * 64 + s * 32); o = __builtin_amdgcn_mfma_f32_32x32x16_bf16(vf, __builtin_bit_cast(bf16x8, pw[kb][s]), o, 0, 0, 0); }
; #pragma unroll
;         for (int g4 = 0; g4 < 4; ++g4) { u32x2 w; w.x = cvtpk(o[4 * g4] * rl, o[4 * g4 + 1] * rl); w.y = cvtpk(o[4 * g4 + 2] * rl, o[4 * g4 + 3] * rl);
;             *(XLAS u32x2*)(xs + r32 * 144 + ((db & 1) * 32 + 8 * g4 + 4 * hi) * 2) = w; }
;         if (db & 1) {
; #pragma unroll
;             for (int i = 0; i < 4; ++i) { const u32x4 v = *(const XLAS u32x4*)(xs + (8 * i + (lane >> 3)) * 144 + (lane & 7) * 16); *(u32x4*)(obase + (size_t)(8 * i) * 1024 + (db >> 1) * 64) = v; }
;         }
	ds_read_b128 v[140:143], v99
	ds_read_b128 v[144:147], v99 offset:32
	ds_read_b128 v[148:151], v99 offset:64
	ds_read_b128 v[152:155], v99 offset:96
	ds_read_b128 v[156:159], v99 offset:128
	ds_read_b128 v[160:163], v99 offset:160
	ds_read_b128 v[164:167], v99 offset:192
	ds_read_b128 v[168:171], v99 offset:224
	s_waitcnt lgkmcnt(7)
	v_mfma_f32_32x32x16_bf16 v[2:17], v[140:143], v[130:133], 0
	ds_read_b128 v[140:143], v99 offset:256
	s_waitcnt lgkmcnt(7)
	v_mfma_f32_32x32x16_bf16 v[2:17], v[144:147], v[134:137], v[2:17]
	ds_read_b128 v[144:147], v99 offset:288
	s_waitcnt lgkmcnt(7)
	v_mfma_f32_32x32x16_bf16 v[2:17], v[148:151], v[34:37], v[2:17]
	ds_read_b128 v[148:151], v99 offset:320
	s_waitcnt lgkmcnt(7)
	v_mfma_f32_32x32x16_bf16 v[2:17], v[152:155], v[38:41], v[2:17]
	ds_read_b128 v[152:155], v99 offset:352
	s_waitcnt lgkmcnt(7)
	v_mfma_f32_32x32x16_bf16 v[2:17], v[156:159], v[42:45], v[2:17]
	ds_read_b128 v[156:159], v99 offset:384
	s_waitcnt lgkmcnt(7)
	v_mfma_f32_32x32x16_bf16 v[2:17], v[160:163], v[46:49], v[2:17]
	ds_read_b128 v[160:163], v99 offset:416
	s_waitcnt lgkmcnt(7)
	v_mfma_f32_32x32x16_bf16 v[2:17], v[164:167], v[50:53], v[2:17]
	ds_read_b128 v[164:167], v99 offset:448
	s_waitcnt lgkmcnt(7)
	v_mfma_f32_32x32x16_bf16 v[2:17], v[168:171], v[54:57], v[2:17]
	ds_read_b128 v[168:171], v99 offset:480
	s_waitcnt lgkmcnt(7)
	v_mfma_f32_32x32x16_bf16 v[2:17], v[140:143], v[58:61], v[2:17]
	s_waitcnt lgkmcnt(6)
	v_mfma_f32_32x32x16_bf16 v[2:17], v[144:147], v[62:65], v[2:17]
	s_waitcnt lgkmcnt(5)
	v_mfma_f32_32x32x16_bf16 v[2:17], v[148:151], v[66:69], v[2:17]
	s_waitcnt lgkmcnt(4)
	v_mfma_f32_32x32x16_bf16 v[2:17], v[152:155], v[70:73], v[2:17]
	s_waitcnt lgkmcnt(3)
	v_mfma_f32_32x32x16_bf16 v[2:17], v[156:159], v[74:77], v[2:17]
	s_waitcnt lgkmcnt(2)
	v_mfma_f32_32x32x16_bf16 v[2:17], v[160:163], v[78:81], v[2:17]
	s_waitcnt lgkmcnt(1)
	v_mfma_f32_32x32x16_bf16 v[2:17], v[164:167], v[86:89], v[2:17]
	v_add_co_u32_e32 v20, vcc, s17, v212
	v_lshl_add_u64 v[18:19], v[212:213], 0, s[30:31]
	s_nop 0
	v_addc_co_u32_e32 v21, vcc, 0, v213, vcc
	global_load_dwordx4 v[22:25], v[20:21], off
	s_nop 0
	global_load_dwordx4 v[18:21], v[18:19], off offset:16
	s_waitcnt lgkmcnt(0)
	v_mfma_f32_32x32x16_bf16 v[2:17], v[168:171], v[82:85], v[2:17]
	s_nop 11
	v_pk_mul_f32 v[2:3], v[2:3], v[98:99] op_sel_hi:[1,0]
	v_pk_mul_f32 v[4:5], v[4:5], v[98:99] op_sel_hi:[1,0]
	v_cvt_pk_bf16_f32 v2, v2, v3
	v_cvt_pk_bf16_f32 v3, v4, v5
	v_pk_mul_f32 v[4:5], v[6:7], v[98:99] op_sel_hi:[1,0]
	v_pk_mul_f32 v[6:7], v[8:9], v[98:99] op_sel_hi:[1,0]
	v_cvt_pk_bf16_f32 v4, v4, v5
	v_cvt_pk_bf16_f32 v5, v6, v7
	ds_write2_b64 v100, v[2:3], v[4:5] offset1:2
	v_pk_mul_f32 v[2:3], v[10:11], v[98:99] op_sel_hi:[1,0]
	v_pk_mul_f32 v[4:5], v[12:13], v[98:99] op_sel_hi:[1,0]
	v_cvt_pk_bf16_f32 v2, v2, v3
	v_cvt_pk_bf16_f32 v3, v4, v5
	v_pk_mul_f32 v[4:5], v[14:15], v[98:99] op_sel_hi:[1,0]
	v_pk_mul_f32 v[6:7], v[16:17], v[98:99] op_sel_hi:[1,0]
	v_cvt_pk_bf16_f32 v4, v4, v5
	v_cvt_pk_bf16_f32 v5, v6, v7
	ds_write2_b64 v100, v[2:3], v[4:5] offset0:4 offset1:6
	s_waitcnt vmcnt(7)
	ds_write_b128 v214, v[102:105] offset:16896
	s_waitcnt vmcnt(6)
	ds_write_b128 v214, v[106:109] offset:16912
	s_waitcnt lgkmcnt(0)
	s_barrier
	ds_read_b128 v[140:143], v99 offset:16896
	ds_read_b128 v[144:147], v99 offset:16928
	ds_read_b128 v[148:151], v99 offset:16960
	ds_read_b128 v[152:155], v99 offset:16992
	ds_read_b128 v[156:159], v99 offset:17024
	ds_read_b128 v[160:163], v99 offset:17056
	ds_read_b128 v[164:167], v99 offset:17088
	ds_read_b128 v[168:171], v99 offset:17120
	s_waitcnt lgkmcnt(7)
	v_mfma_f32_32x32x16_bf16 v[2:17], v[140:143], v[130:133], 0
	ds_read_b128 v[140:143], v99 offset:17152
	v_lshl_add_u64 v[102:103], v[212:213], 0, s[38:39]
	s_waitcnt lgkmcnt(7)
	v_mfma_f32_32x32x16_bf16 v[2:17], v[144:147], v[134:137], v[2:17]
	ds_read_b128 v[144:147], v99 offset:17184
	s_waitcnt lgkmcnt(7)
	v_mfma_f32_32x32x16_bf16 v[2:17], v[148:151], v[34:37], v[2:17]
	ds_read_b128 v[148:151], v99 offset:17216
	s_waitcnt lgkmcnt(7)
	v_mfma_f32_32x32x16_bf16 v[2:17], v[152:155], v[38:41], v[2:17]
	ds_read_b128 v[152:155], v99 offset:17248
	s_waitcnt lgkmcnt(7)
	v_mfma_f32_32x32x16_bf16 v[2:17], v[156:159], v[42:45], v[2:17]
	ds_read_b128 v[156:159], v99 offset:17280
	s_waitcnt lgkmcnt(7)
	v_mfma_f32_32x32x16_bf16 v[2:17], v[160:163], v[46:49], v[2:17]
	ds_read_b128 v[160:163], v99 offset:17312
	s_waitcnt lgkmcnt(7)
	v_mfma_f32_32x32x16_bf16 v[2:17], v[164:167], v[50:53], v[2:17]
	ds_read_b128 v[164:167], v99 offset:17344
	s_waitcnt lgkmcnt(7)
	v_mfma_f32_32x32x16_bf16 v[2:17], v[168:171], v[54:57], v[2:17]
	ds_read_b128 v[168:171], v99 offset:17376
	s_waitcnt lgkmcnt(7)
	v_mfma_f32_32x32x16_bf16 v[2:17], v[140:143], v[58:61], v[2:17]
	s_waitcnt lgkmcnt(6)
	v_mfma_f32_32x32x16_bf16 v[2:17], v[144:147], v[62:65], v[2:17]
	s_waitcnt lgkmcnt(5)
	v_mfma_f32_32x32x16_bf16 v[2:17], v[148:151], v[66:69], v[2:17]
	s_waitcnt lgkmcnt(4)
	v_mfma_f32_32x32x16_bf16 v[2:17], v[152:155], v[70:73], v[2:17]
	s_waitcnt lgkmcnt(3)
	v_mfma_f32_32x32x16_bf16 v[2:17], v[156:159], v[74:77], v[2:17]
	s_waitcnt lgkmcnt(2)
	v_mfma_f32_32x32x16_bf16 v[2:17], v[160:163], v[78:81], v[2:17]
	s_waitcnt lgkmcnt(1)
	v_mfma_f32_32x32x16_bf16 v[2:17], v[164:167], v[86:89], v[2:17]
	v_add_co_u32_e32 v90, vcc, s27, v212
	s_nop 1
	v_addc_co_u32_e32 v91, vcc, 0, v213, vcc
	s_waitcnt lgkmcnt(0)
	v_mfma_f32_32x32x16_bf16 v[2:17], v[168:171], v[82:85], v[2:17]
	s_nop 11
	v_pk_mul_f32 v[2:3], v[98:99], v[2:3] op_sel_hi:[0,1]
	v_pk_mul_f32 v[4:5], v[98:99], v[4:5] op_sel_hi:[0,1]
	v_cvt_pk_bf16_f32 v2, v2, v3
	v_cvt_pk_bf16_f32 v3, v4, v5
	v_pk_mul_f32 v[4:5], v[98:99], v[6:7] op_sel_hi:[0,1]
	v_pk_mul_f32 v[6:7], v[98:99], v[8:9] op_sel_hi:[0,1]
	v_cvt_pk_bf16_f32 v4, v4, v5
	v_cvt_pk_bf16_f32 v5, v6, v7
	ds_write2_b64 v100, v[2:3], v[4:5] offset0:8 offset1:10
	v_pk_mul_f32 v[2:3], v[98:99], v[10:11] op_sel_hi:[0,1]
	v_pk_mul_f32 v[4:5], v[98:99], v[12:13] op_sel_hi:[0,1]
	v_cvt_pk_bf16_f32 v2, v2, v3
	v_cvt_pk_bf16_f32 v3, v4, v5
	v_pk_mul_f32 v[4:5], v[98:99], v[14:15] op_sel_hi:[0,1]
	v_pk_mul_f32 v[6:7], v[98:99], v[16:17] op_sel_hi:[0,1]
	v_cvt_pk_bf16_f32 v4, v4, v5
	v_cvt_pk_bf16_f32 v5, v6, v7
	ds_write2_b64 v100, v[2:3], v[4:5] offset0:12 offset1:14
	ds_read_b128 v[2:5], v0 offset:34816
	ds_read_b128 v[6:9], v0 offset:35968
	ds_read_b128 v[10:13], v0 offset:37120
	ds_read_b128 v[14:17], v0 offset:38272
	global_load_dwordx4 v[90:93], v[90:91], off
	s_nop 0
	global_load_dwordx4 v[94:97], v[102:103], off offset:16
	s_waitcnt lgkmcnt(3)
	global_store_dwordx4 v[26:27], v[2:5], off offset:128
	s_waitcnt lgkmcnt(2)
	global_store_dwordx4 v[28:29], v[6:9], off offset:128
	s_waitcnt lgkmcnt(1)
	global_store_dwordx4 v[30:31], v[10:13], off offset:128
	s_waitcnt lgkmcnt(0)
	global_store_dwordx4 v[32:33], v[14:17], off offset:128
	s_waitcnt vmcnt(7)
	ds_write_b128 v214, v[22:25]
	s_waitcnt vmcnt(6)
	ds_write_b128 v214, v[18:21] offset:16
	s_waitcnt lgkmcnt(0)
	s_barrier
; #define XLAS __attribute__((address_space(3)))
; __device__ __forceinline__ unsigned cvtpk(float lo, float hi) { f32x2_t v = {lo, hi}; bf16x2_t b = __builtin_convertvector(v, bf16x2_t); return __builtin_bit_cast(unsigned, b); }
; __device__ __forceinline__ void unit(XLAS unsigned char* lds, const bf16_t* Qg, const bf16_t* Kg, const bf16_t* Vg, bf16_t* Og) {
;     ...
;     for (int db = 0; db < 8; ++db) {
;         XLAS unsigned char* buf = lds + (db & 1) * CHB;
;         *(XLAS u32x4*)(buf + wofs) = g[db & 1][0]; *(XLAS u32x4*)(buf + wofs + 16) = g[db & 1][1];
;         __syncthreads();
;         if (db < 6) { g[db & 1][0] = *(const u32x4*)(XAT_SRC(db + 10)); g[db & 1][1] = *(const u32x4*)(XAT_SRC(db + 10) + 8); }
;         f32x16 o = {};
; #pragma unroll
;         for (int kb = 0; kb < 8; ++kb)
; #pragma unroll
;             for (int s = 0; s < 2; ++s) { const bf16x8 vf = *(const XLAS bf16x8*)(buf + vro + kb * 64 + s * 32); o = __builtin_amdgcn_mfma_f32_32x32x16_bf16(vf, __builtin_bit_cast(bf16x8, pw[kb][s]), o, 0, 0, 0); }
; #pragma unroll
;         for (int g4 = 0; g4 < 4; ++g4) { u32x2 w; w.x = cvtpk(o[4 * g4] * rl, o[4 * g4 + 1] * rl); w.y = cvtpk(o[4 * g4 + 2] * rl, o[4 * g4 + 3] * rl);
;             *(XLAS u32x2*)(xs + r32 * 144 + ((db & 1) * 32 + 8 * g4 + 4 * hi) * 2) = w; }
;         if (db & 1) {
; #pragma unroll
;             for (int i = 0; i < 4; ++i) { const u32x4 v = *(const XLAS u32x4*)(xs + (8 * i + (lane >> 3)) * 144 + (lane & 7) * 16); *(u32x4*)(obase + (size_t)(8 * i) * 1024 + (db >> 1) * 64) = v; }
;         }
	ds_read_b128 v[140:143], v99
	ds_read_b128 v[144:147], v99 offset:32
	ds_read_b128 v[148:151], v99 offset:64
	ds_read_b128 v[152:155], v99 offset:96
	ds_read_b128 v[156:159], v99 offset:128
	ds_read_b128 v[160:163], v99 offset:160
	ds_read_b128 v[164:167], v99 offset:192
	ds_read_b128 v[168:171], v99 offset:224
	s_waitcnt lgkmcnt(7)
	v_mfma_f32_32x32x16_bf16 v[2:17], v[140:143], v[130:133], 0
	ds_read_b128 v[140:143], v99 offset:256
	s_waitcnt lgkmcnt(7)
	v_mfma_f32_32x32x16_bf16 v[2:17], v[144:147], v[134:137], v[2:17]
	ds_read_b128 v[144:147], v99 offset:288
	s_waitcnt lgkmcnt(7)
	v_mfma_f32_32x32x16_bf16 v[2:17], v[148:151], v[34:37], v[2:17]
	ds_read_b128 v[148:151], v99 offset:320
	s_waitcnt lgkmcnt(7)
	v_mfma_f32_32x32x16_bf16 v[2:17], v[152:155], v[38:41], v[2:17]
	ds_read_b128 v[152:155], v99 offset:352
	s_waitcnt lgkmcnt(7)
	v_mfma_f32_32x32x16_bf16 v[2:17], v[156:159], v[42:45], v[2:17]
	ds_read_b128 v[156:159], v99 offset:384
	s_waitcnt lgkmcnt(7)
	v_mfma_f32_32x32x16_bf16 v[2:17], v[160:163], v[46:49], v[2:17]
	ds_read_b128 v[160:163], v99 offset:416
	s_waitcnt lgkmcnt(7)
	v_mfma_f32_32x32x16_bf16 v[2:17], v[164:167], v[50:53], v[2:17]
	ds_read_b128 v[164:167], v99 offset:448
	s_waitcnt lgkmcnt(7)
	v_mfma_f32_32x32x16_bf16 v[2:17], v[168:171], v[54:57], v[2:17]
	ds_read_b128 v[168:171], v99 offset:480
	s_waitcnt lgkmcnt(7)
	v_mfma_f32_32x32x16_bf16 v[2:17], v[140:143], v[58:61], v[2:17]
	s_waitcnt lgkmcnt(6)
	v_mfma_f32_32x32x16_bf16 v[2:17], v[144:147], v[62:65], v[2:17]
	s_waitcnt lgkmcnt(5)
	v_mfma_f32_32x32x16_bf16 v[2:17], v[148:151], v[66:69], v[2:17]
	s_waitcnt lgkmcnt(4)
	v_mfma_f32_32x32x16_bf16 v[2:17], v[152:155], v[70:73], v[2:17]
	s_waitcnt lgkmcnt(3)
	v_mfma_f32_32x32x16_bf16 v[2:17], v[156:159], v[74:77], v[2:17]
	s_waitcnt lgkmcnt(2)
	v_mfma_f32_32x32x16_bf16 v[2:17], v[160:163], v[78:81], v[2:17]
	s_waitcnt lgkmcnt(1)
	v_mfma_f32_32x32x16_bf16 v[2:17], v[164:167], v[86:89], v[2:17]
	v_add_co_u32_e32 v20, vcc, s58, v212
	v_lshl_add_u64 v[18:19], v[212:213], 0, s[56:57]
	s_nop 0
	v_addc_co_u32_e32 v21, vcc, 0, v213, vcc
	global_load_dwordx4 v[22:25], v[20:21], off
	s_nop 0
	global_load_dwordx4 v[18:21], v[18:19], off offset:16
	s_waitcnt lgkmcnt(0)
	v_mfma_f32_32x32x16_bf16 v[2:17], v[168:171], v[82:85], v[2:17]
	v_lshl_add_u64 v[102:103], v[212:213], 0, s[60:61]
	s_nop 10
	v_pk_mul_f32 v[2:3], v[98:99], v[2:3] op_sel_hi:[0,1]
	v_pk_mul_f32 v[4:5], v[98:99], v[4:5] op_sel_hi:[0,1]
	v_cvt_pk_bf16_f32 v2, v2, v3
	v_cvt_pk_bf16_f32 v3, v4, v5
	v_pk_mul_f32 v[4:5], v[98:99], v[6:7] op_sel_hi:[0,1]
	v_pk_mul_f32 v[6:7], v[98:99], v[8:9] op_sel_hi:[0,1]
	v_cvt_pk_bf16_f32 v4, v4, v5
	v_cvt_pk_bf16_f32 v5, v6, v7
	ds_write2_b64 v100, v[2:3], v[4:5] offset1:2
	v_pk_mul_f32 v[2:3], v[98:99], v[10:11] op_sel_hi:[0,1]
	v_pk_mul_f32 v[4:5], v[98:99], v[12:13] op_sel_hi:[0,1]
	v_cvt_pk_bf16_f32 v2, v2, v3
	v_cvt_pk_bf16_f32 v3, v4, v5
	v_pk_mul_f32 v[4:5], v[98:99], v[14:15] op_sel_hi:[0,1]
	v_pk_mul_f32 v[6:7], v[98:99], v[16:17] op_sel_hi:[0,1]
	v_cvt_pk_bf16_f32 v4, v4, v5
	v_cvt_pk_bf16_f32 v5, v6, v7
	ds_write2_b64 v100, v[2:3], v[4:5] offset0:4 offset1:6
	s_waitcnt vmcnt(7)
	ds_write_b128 v214, v[90:93] offset:16896
	s_waitcnt vmcnt(6)
	ds_write_b128 v214, v[94:97] offset:16912
	s_waitcnt lgkmcnt(0)
	s_barrier
	ds_read_b128 v[140:143], v99 offset:16896
	ds_read_b128 v[144:147], v99 offset:16928
	ds_read_b128 v[148:151], v99 offset:16960
	ds_read_b128 v[152:155], v99 offset:16992
	ds_read_b128 v[156:159], v99 offset:17024
	ds_read_b128 v[160:163], v99 offset:17056
	ds_read_b128 v[164:167], v99 offset:17088
	ds_read_b128 v[168:171], v99 offset:17120
	s_waitcnt lgkmcnt(7)
	v_mfma_f32_32x32x16_bf16 v[2:17], v[140:143], v[130:133], 0
	ds_read_b128 v[140:143], v99 offset:17152
	s_waitcnt lgkmcnt(7)
	v_mfma_f32_32x32x16_bf16 v[2:17], v[144:147], v[134:137], v[2:17]
	ds_read_b128 v[144:147], v99 offset:17184
	s_waitcnt lgkmcnt(7)
	v_mfma_f32_32x32x16_bf16 v[2:17], v[148:151], v[34:37], v[2:17]
	ds_read_b128 v[148:151], v99 offset:17216
	s_waitcnt lgkmcnt(7)
	v_mfma_f32_32x32x16_bf16 v[2:17], v[152:155], v[38:41], v[2:17]
	ds_read_b128 v[152:155], v99 offset:17248
	s_waitcnt lgkmcnt(7)
	v_mfma_f32_32x32x16_bf16 v[2:17], v[156:159], v[42:45], v[2:17]
	ds_read_b128 v[156:159], v99 offset:17280
	s_waitcnt lgkmcnt(7)
	v_mfma_f32_32x32x16_bf16 v[2:17], v[160:163], v[46:49], v[2:17]
	ds_read_b128 v[160:163], v99 offset:17312
	s_waitcnt lgkmcnt(7)
	v_mfma_f32_32x32x16_bf16 v[2:17], v[164:167], v[50:53], v[2:17]
	ds_read_b128 v[164:167], v99 offset:17344
	s_waitcnt lgkmcnt(7)
	v_mfma_f32_32x32x16_bf16 v[2:17], v[168:171], v[54:57], v[2:17]
	ds_read_b128 v[168:171], v99 offset:17376
	s_waitcnt lgkmcnt(7)
	v_mfma_f32_32x32x16_bf16 v[2:17], v[140:143], v[58:61], v[2:17]
	s_waitcnt lgkmcnt(6)
	v_mfma_f32_32x32x16_bf16 v[2:17], v[144:147], v[62:65], v[2:17]
	s_waitcnt lgkmcnt(5)
	v_mfma_f32_32x32x16_bf16 v[2:17], v[148:151], v[66:69], v[2:17]
	s_waitcnt lgkmcnt(4)
	v_mfma_f32_32x32x16_bf16 v[2:17], v[152:155], v[70:73], v[2:17]
	s_waitcnt lgkmcnt(3)
	v_mfma_f32_32x32x16_bf16 v[2:17], v[156:159], v[74:77], v[2:17]
	s_waitcnt lgkmcnt(2)
	v_mfma_f32_32x32x16_bf16 v[2:17], v[160:163], v[78:81], v[2:17]
	s_waitcnt lgkmcnt(1)
	v_mfma_f32_32x32x16_bf16 v[2:17], v[164:167], v[86:89], v[2:17]
	v_add_co_u32_e32 v90, vcc, s59, v212
	s_nop 1
	v_addc_co_u32_e32 v91, vcc, 0, v213, vcc
	s_waitcnt lgkmcnt(0)
	v_mfma_f32_32x32x16_bf16 v[2:17], v[168:171], v[82:85], v[2:17]
	s_nop 11
	v_pk_mul_f32 v[2:3], v[98:99], v[2:3] op_sel_hi:[0,1]
	v_pk_mul_f32 v[4:5], v[98:99], v[4:5] op_sel_hi:[0,1]
	v_cvt_pk_bf16_f32 v2, v2, v3
	v_cvt_pk_bf16_f32 v3, v4, v5
	v_pk_mul_f32 v[4:5], v[98:99], v[6:7] op_sel_hi:[0,1]
	v_pk_mul_f32 v[6:7], v[98:99], v[8:9] op_sel_hi:[0,1]
	v_cvt_pk_bf16_f32 v4, v4, v5
	v_cvt_pk_bf16_f32 v5, v6, v7
	ds_write2_b64 v100, v[2:3], v[4:5] offset0:8 offset1:10
	v_pk_mul_f32 v[2:3], v[98:99], v[10:11] op_sel_hi:[0,1]
	v_pk_mul_f32 v[4:5], v[98:99], v[12:13] op_sel_hi:[0,1]
	v_cvt_pk_bf16_f32 v2, v2, v3
	v_cvt_pk_bf16_f32 v3, v4, v5
	v_pk_mul_f32 v[4:5], v[98:99], v[14:15] op_sel_hi:[0,1]
	v_pk_mul_f32 v[6:7], v[98:99], v[16:17] op_sel_hi:[0,1]
	v_cvt_pk_bf16_f32 v4, v4, v5
	v_cvt_pk_bf16_f32 v5, v6, v7
	ds_write2_b64 v100, v[2:3], v[4:5] offset0:12 offset1:14
	ds_read_b128 v[2:5], v0 offset:34816
	ds_read_b128 v[6:9], v0 offset:35968
	ds_read_b128 v[10:13], v0 offset:37120
	ds_read_b128 v[14:17], v0 offset:38272
	global_load_dwordx4 v[90:93], v[90:91], off
	s_nop 0
	global_load_dwordx4 v[94:97], v[102:103], off offset:16
	s_waitcnt lgkmcnt(3)
	global_store_dwordx4 v[26:27], v[2:5], off offset:256
	s_waitcnt lgkmcnt(2)
	global_store_dwordx4 v[28:29], v[6:9], off offset:256
	s_waitcnt lgkmcnt(1)
	global_store_dwordx4 v[30:31], v[10:13], off offset:256
	s_waitcnt lgkmcnt(0)
	global_store_dwordx4 v[32:33], v[14:17], off offset:256
	s_waitcnt vmcnt(7)
	ds_write_b128 v214, v[22:25]
	s_waitcnt vmcnt(6)
	ds_write_b128 v214, v[18:21] offset:16
	s_waitcnt lgkmcnt(0)
	s_barrier
; #define XLAS __attribute__((address_space(3)))
; __device__ __forceinline__ unsigned cvtpk(float lo, float hi) { f32x2_t v = {lo, hi}; bf16x2_t b = __builtin_convertvector(v, bf16x2_t); return __builtin_bit_cast(unsigned, b); }
; __device__ __forceinline__ void unit(XLAS unsigned char* lds, const bf16_t* Qg, const bf16_t* Kg, const bf16_t* Vg, bf16_t* Og) {
;     ...
;     for (int db = 0; db < 8; ++db) {
;         XLAS unsigned char* buf = lds + (db & 1) * CHB;
;         *(XLAS u32x4*)(buf + wofs) = g[db & 1][0]; *(XLAS u32x4*)(buf + wofs + 16) = g[db & 1][1];
;         __syncthreads();
;         if (db < 6) { g[db & 1][0] = *(const u32x4*)(XAT_SRC(db + 10)); g[db & 1][1] = *(const u32x4*)(XAT_SRC(db + 10) + 8); }
;         f32x16 o = {};
; #pragma unroll
;         for (int kb = 0; kb < 8; ++kb)
; #pragma unroll
;             for (int s = 0; s < 2; ++s) { const bf16x8 vf = *(const XLAS bf16x8*)(buf + vro + kb * 64 + s * 32); o = __builtin_amdgcn_mfma_f32_32x32x16_bf16(vf, __builtin_bit_cast(bf16x8, pw[kb][s]), o, 0, 0, 0); }
; #pragma unroll
;         for (int g4 = 0; g4 < 4; ++g4) { u32x2 w; w.x = cvtpk(o[4 * g4] * rl, o[4 * g4 + 1] * rl); w.y = cvtpk(o[4 * g4 + 2] * rl, o[4 * g4 + 3] * rl);
;             *(XLAS u32x2*)(xs + r32 * 144 + ((db & 1) * 32 + 8 * g4 + 4 * hi) * 2) = w; }
;         if (db & 1) {
; #pragma unroll
;             for (int i = 0; i < 4; ++i) { const u32x4 v = *(const XLAS u32x4*)(xs + (8 * i + (lane >> 3)) * 144 + (lane & 7) * 16); *(u32x4*)(obase + (size_t)(8 * i) * 1024 + (db >> 1) * 64) = v; }
;         }
	ds_read_b128 v[140:143], v99
	ds_read_b128 v[144:147], v99 offset:32
	ds_read_b128 v[148:151], v99 offset:64
	ds_read_b128 v[152:155], v99 offset:96
	ds_read_b128 v[156:159], v99 offset:128
	ds_read_b128 v[160:163], v99 offset:160
	ds_read_b128 v[164:167], v99 offset:192
	ds_read_b128 v[168:171], v99 offset:224
	s_waitcnt lgkmcnt(7)
	v_mfma_f32_32x32x16_bf16 v[2:17], v[140:143], v[130:133], 0
	ds_read_b128 v[140:143], v99 offset:256
	s_waitcnt lgkmcnt(7)
	v_mfma_f32_32x32x16_bf16 v[2:17], v[144:147], v[134:137], v[2:17]
	ds_read_b128 v[144:147], v99 offset:288
	s_waitcnt lgkmcnt(7)
	v_mfma_f32_32x32x16_bf16 v[2:17], v[148:151], v[34:37], v[2:17]
	ds_read_b128 v[148:151], v99 offset:320
	s_waitcnt lgkmcnt(7)
	v_mfma_f32_32x32x16_bf16 v[2:17], v[152:155], v[38:41], v[2:17]
	ds_read_b128 v[152:155], v99 offset:352
	s_waitcnt lgkmcnt(7)
	v_mfma_f32_32x32x16_bf16 v[2:17], v[156:159], v[42:45], v[2:17]
	ds_read_b128 v[156:159], v99 offset:384
	s_waitcnt lgkmcnt(7)
	v_mfma_f32_32x32x16_bf16 v[2:17], v[160:163], v[46:49], v[2:17]
	ds_read_b128 v[160:163], v99 offset:416
	s_waitcnt lgkmcnt(7)
	v_mfma_f32_32x32x16_bf16 v[2:17], v[164:167], v[50:53], v[2:17]
	ds_read_b128 v[164:167], v99 offset:448
	s_waitcnt lgkmcnt(7)
	v_mfma_f32_32x32x16_bf16 v[2:17], v[168:171], v[54:57], v[2:17]
	ds_read_b128 v[168:171], v99 offset:480
	s_waitcnt lgkmcnt(7)
	v_mfma_f32_32x32x16_bf16 v[2:17], v[140:143], v[58:61], v[2:17]
	s_waitcnt lgkmcnt(6)
	v_mfma_f32_32x32x16_bf16 v[2:17], v[144:147], v[62:65], v[2:17]
	s_waitcnt lgkmcnt(5)
	v_mfma_f32_32x32x16_bf16 v[2:17], v[148:151], v[66:69], v[2:17]
	s_waitcnt lgkmcnt(4)
	v_mfma_f32_32x32x16_bf16 v[2:17], v[152:155], v[70:73], v[2:17]
	s_waitcnt lgkmcnt(3)
	v_mfma_f32_32x32x16_bf16 v[2:17], v[156:159], v[74:77], v[2:17]
	s_waitcnt lgkmcnt(2)
	v_mfma_f32_32x32x16_bf16 v[2:17], v[160:163], v[78:81], v[2:17]
	s_waitcnt lgkmcnt(1)
	v_mfma_f32_32x32x16_bf16 v[2:17], v[164:167], v[86:89], v[2:17]
	s_waitcnt lgkmcnt(0)
	v_mfma_f32_32x32x16_bf16 v[2:17], v[168:171], v[82:85], v[2:17]
	s_nop 11
	v_pk_mul_f32 v[2:3], v[98:99], v[2:3] op_sel_hi:[0,1]
	v_pk_mul_f32 v[4:5], v[98:99], v[4:5] op_sel_hi:[0,1]
	v_pk_mul_f32 v[6:7], v[98:99], v[6:7] op_sel_hi:[0,1]
	v_pk_mul_f32 v[8:9], v[98:99], v[8:9] op_sel_hi:[0,1]
	v_pk_mul_f32 v[10:11], v[98:99], v[10:11] op_sel_hi:[0,1]
	v_pk_mul_f32 v[12:13], v[98:99], v[12:13] op_sel_hi:[0,1]
	v_pk_mul_f32 v[14:15], v[98:99], v[14:15] op_sel_hi:[0,1]
	v_pk_mul_f32 v[16:17], v[98:99], v[16:17] op_sel_hi:[0,1]
	v_cvt_pk_bf16_f32 v2, v2, v3
	v_cvt_pk_bf16_f32 v3, v4, v5
	v_cvt_pk_bf16_f32 v4, v6, v7
	v_cvt_pk_bf16_f32 v5, v8, v9
	v_cvt_pk_bf16_f32 v6, v10, v11
	v_cvt_pk_bf16_f32 v7, v12, v13
	v_cvt_pk_bf16_f32 v8, v14, v15
	v_cvt_pk_bf16_f32 v9, v16, v17
	ds_write2_b64 v100, v[2:3], v[4:5] offset1:2
	ds_write2_b64 v100, v[6:7], v[8:9] offset0:4 offset1:6
	s_waitcnt vmcnt(5)
	ds_write_b128 v214, v[90:93] offset:16896
	s_waitcnt vmcnt(4)
	ds_write_b128 v214, v[94:97] offset:16912
	s_waitcnt lgkmcnt(0)
	s_barrier
	ds_read_b128 v[140:143], v99 offset:16896
	ds_read_b128 v[144:147], v99 offset:16928
	ds_read_b128 v[148:151], v99 offset:16960
	ds_read_b128 v[152:155], v99 offset:16992
	ds_read_b128 v[156:159], v99 offset:17024
	ds_read_b128 v[160:163], v99 offset:17056
	ds_read_b128 v[164:167], v99 offset:17088
	ds_read_b128 v[168:171], v99 offset:17120
	s_waitcnt lgkmcnt(7)
	v_mfma_f32_32x32x16_bf16 v[2:17], v[140:143], v[130:133], 0
	ds_read_b128 v[140:143], v99 offset:17152
	s_waitcnt lgkmcnt(7)
	v_mfma_f32_32x32x16_bf16 v[2:17], v[144:147], v[134:137], v[2:17]
	ds_read_b128 v[144:147], v99 offset:17184
	s_waitcnt lgkmcnt(7)
	v_mfma_f32_32x32x16_bf16 v[2:17], v[148:151], v[34:37], v[2:17]
	ds_read_b128 v[148:151], v99 offset:17216
	s_waitcnt lgkmcnt(7)
	v_mfma_f32_32x32x16_bf16 v[2:17], v[152:155], v[38:41], v[2:17]
	ds_read_b128 v[152:155], v99 offset:17248
	s_waitcnt lgkmcnt(7)
	v_mfma_f32_32x32x16_bf16 v[2:17], v[156:159], v[42:45], v[2:17]
	ds_read_b128 v[156:159], v99 offset:17280
	s_waitcnt lgkmcnt(7)
	v_mfma_f32_32x32x16_bf16 v[2:17], v[160:163], v[46:49], v[2:17]
	ds_read_b128 v[160:163], v99 offset:17312
	s_waitcnt lgkmcnt(7)
	v_mfma_f32_32x32x16_bf16 v[2:17], v[164:167], v[50:53], v[2:17]
	ds_read_b128 v[164:167], v99 offset:17344
	s_waitcnt lgkmcnt(7)
	v_mfma_f32_32x32x16_bf16 v[2:17], v[168:171], v[54:57], v[2:17]
	ds_read_b128 v[168:171], v99 offset:17376
	s_waitcnt lgkmcnt(7)
	v_mfma_f32_32x32x16_bf16 v[2:17], v[140:143], v[58:61], v[2:17]
	s_waitcnt lgkmcnt(6)
	v_mfma_f32_32x32x16_bf16 v[2:17], v[144:147], v[62:65], v[2:17]
	s_waitcnt lgkmcnt(5)
	v_mfma_f32_32x32x16_bf16 v[2:17], v[148:151], v[66:69], v[2:17]
	s_waitcnt lgkmcnt(4)
	v_mfma_f32_32x32x16_bf16 v[2:17], v[152:155], v[70:73], v[2:17]
	s_waitcnt lgkmcnt(3)
	v_mfma_f32_32x32x16_bf16 v[2:17], v[156:159], v[74:77], v[2:17]
	s_waitcnt lgkmcnt(2)
	v_mfma_f32_32x32x16_bf16 v[2:17], v[160:163], v[78:81], v[2:17]
	s_waitcnt lgkmcnt(1)
	v_mfma_f32_32x32x16_bf16 v[2:17], v[164:167], v[86:89], v[2:17]
	s_waitcnt lgkmcnt(0)
	v_mfma_f32_32x32x16_bf16 v[2:17], v[168:171], v[82:85], v[2:17]
	s_nop 11
	v_pk_mul_f32 v[2:3], v[98:99], v[2:3] op_sel_hi:[0,1]
	v_pk_mul_f32 v[4:5], v[98:99], v[4:5] op_sel_hi:[0,1]
	v_pk_mul_f32 v[6:7], v[98:99], v[6:7] op_sel_hi:[0,1]
	v_pk_mul_f32 v[8:9], v[98:99], v[8:9] op_sel_hi:[0,1]
	v_pk_mul_f32 v[10:11], v[98:99], v[10:11] op_sel_hi:[0,1]
	v_pk_mul_f32 v[12:13], v[98:99], v[12:13] op_sel_hi:[0,1]
	v_pk_mul_f32 v[14:15], v[98:99], v[14:15] op_sel_hi:[0,1]
	v_pk_mul_f32 v[16:17], v[98:99], v[16:17] op_sel_hi:[0,1]
	v_cvt_pk_bf16_f32 v2, v2, v3
	v_cvt_pk_bf16_f32 v3, v4, v5
	v_cvt_pk_bf16_f32 v4, v6, v7
	v_cvt_pk_bf16_f32 v5, v8, v9
	v_cvt_pk_bf16_f32 v6, v10, v11
	v_cvt_pk_bf16_f32 v7, v12, v13
	v_cvt_pk_bf16_f32 v8, v14, v15
	v_cvt_pk_bf16_f32 v9, v16, v17
	ds_write2_b64 v100, v[2:3], v[4:5] offset0:8 offset1:10
	ds_write2_b64 v100, v[6:7], v[8:9] offset0:12 offset1:14
	ds_read_b128 v[2:5], v0 offset:34816
	ds_read_b128 v[6:9], v0 offset:35968
	ds_read_b128 v[10:13], v0 offset:37120
	ds_read_b128 v[14:17], v0 offset:38272
	s_waitcnt lgkmcnt(3)
	global_store_dwordx4 v[26:27], v[2:5], off offset:384
	s_waitcnt lgkmcnt(2)
	global_store_dwordx4 v[28:29], v[6:9], off offset:384
	s_waitcnt lgkmcnt(1)
	global_store_dwordx4 v[30:31], v[10:13], off offset:384
	s_waitcnt lgkmcnt(0)
	global_store_dwordx4 v[32:33], v[14:17], off offset:384
	s_branch .LBB0_585

; #define LAS __attribute__((address_space(3)))
; __device__ __forceinline__ unsigned xb_add(unsigned* p, unsigned v) { return __hip_atomic_fetch_add(p, v, __ATOMIC_RELAXED, __HIP_MEMORY_SCOPE_AGENT); }
; __device__ __forceinline__ unsigned xb_xcc_id() { return (unsigned)__builtin_amdgcn_s_getreg((3 << 11) | 20) & 0xFu; }
; __device__ __forceinline__ void xcd_barrier(const XcdBarrier& b) {
;     asm volatile("s_waitcnt vmcnt(0)" ::: "memory");
;     __syncthreads();
;     if (threadIdx.x == 0) {
;         unsigned* bar = b.bar;
;         __builtin_amdgcn_s_waitcnt(0);
;         unsigned nloc = b.st[0], nx = b.st[1];
;         if (nloc == 0u) { xcd_barrier_complete(bar, b.x, nloc, nx); b.st[0] = nloc; b.st[1] = nx; }
;         const unsigned old = xb_add(&bar[XB_XSUB(b.x)], 1u);
; __global__ void __launch_bounds__(NWAVES * 64, 2) trunk_fwd(Args args) {
;     ...
;         if (ph + 1 < ph_hi) { XcdBarrier xb_; xb_.bar = (unsigned*)ws; xb_.x = xb_xcc_id(); xb_.st = (volatile LAS unsigned*)(L + XB_ST_OFF); xcd_barrier(xb_); }
.LBB0_600:
	s_setprio 0
	v_readlane_b32 s4, v255, 7
	v_readlane_b32 s6, v255, 9
	v_readlane_b32 s7, v255, 10
	s_mov_b64 s[14:15], s[6:7]
	s_add_i32 s14, s14, 1
	v_readlane_b32 s5, v255, 8
	s_mov_b64 s[6:7], s[14:15]
	v_writelane_b32 v255, s4, 7
	s_cmp_ge_i32 s14, s15
	s_nop 0
	v_writelane_b32 v255, s5, 8
	v_writelane_b32 v255, s6, 9
	v_writelane_b32 v255, s7, 10
	s_mov_b64 s[4:5], -1
	s_cbranch_scc1 .LBB0_170
	s_getreg_b32 s0, hwreg(HW_REG_XCC_ID, 0, 4)
	s_waitcnt vmcnt(0)
	s_waitcnt vmcnt(0) lgkmcnt(0)
	s_barrier
	s_mov_b64 s[4:5], exec
	v_readlane_b32 s6, v255, 5
	v_readlane_b32 s7, v255, 6
	s_and_b64 s[6:7], s[4:5], s[6:7]
	s_mov_b64 exec, s[6:7]
	s_cbranch_execz .LBB0_169
	v_readlane_b32 s3, v255, 12
	s_waitcnt vmcnt(0) expcnt(0) lgkmcnt(0)
	s_and_b32 s0, s0, 15
	v_mov_b32_e32 v0, s3
	ds_read_b32 v3, v0
	v_readlane_b32 s3, v255, 13
	s_waitcnt lgkmcnt(0)
	v_cmp_ne_u32_e32 vcc, 0, v3
	v_mov_b32_e32 v0, s3
	ds_read_b32 v0, v0
	s_cbranch_vccnz .LBB0_636
	s_add_u32 s6, s18, 0x1000
	s_addc_u32 s7, s19, 0
	s_add_u32 s8, s18, 0x1100
	s_addc_u32 s9, s19, 0
	s_add_u32 s16, s18, 0x1200
	s_addc_u32 s17, s19, 0
	s_add_u32 s48, s18, 0x1300
	s_addc_u32 s49, s19, 0
	s_mov_b32 s3, 1
	s_branch .LBB0_605
